# attention: XCD-local K/V sharing; tile bodies (dk64 and dk192) with exp/pack pipelined in 4 key slices against the PV MFMAs, DMA issue behind QK MFMAs
# speedup vs baseline: 1.0181x; 1.0112x over previous
; template <int DK>
; DI void attn_pass(const AttnSrc& s, const int q0, const float sc, LAS unsigned char* lds, f32x16 (&O)[4]) {
;     ...
;   const bf16_t* kp[KP]; int kstr[KP]; const bf16_t* vp[2];
; #pragma unroll
;   for (int i = 0; i < KP; ++i) {
;     const int o = (wid + 8 * i) * 1024 + lane * 16, row = o / ROWB, pc = (o % ROWB) >> 4;
;     const int lc = (DK == 64) ? (pc ^ (row & 7)) : ((pc & ~7) | ((pc & 7) ^ ((row >> 1) & 7)));
;     const int e = lc * 8;
;     if (e < s.nk0) { kp[i] = s.k0 + (size_t)row * s.ldk0 + e; kstr[i] = 64 * s.ldk0; } else { kp[i] = s.k1 + (size_t)row * s.ldk1 + (e - s.nk0); kstr[i] = 64 * s.ldk1; }
;   }
; #pragma unroll
;   for (int i = 0; i < 2; ++i) {
;     const int o = (wid + 8 * i) * 1024 + lane * 16, row = o >> 8, pc = (o >> 4) & 15;
;     const int lc = (((pc >> 2) ^ (row & 3)) << 2) | (pc & 3);
;     vp[i] = s.v + (size_t)row * s.ldv + lc * 8;
;   }
;   const int vstr = 64 * s.ldv;
;   const unsigned lds0 = (unsigned)reinterpret_cast<__UINTPTR_TYPE__>(lds);
;   auto issue = [&](int t, int buf) {
; #pragma unroll
;     for (int i = 0; i < KP; ++i) glds16(kp[i] + (size_t)t * kstr[i], (unsigned)__builtin_amdgcn_readfirstlane(lds0 + buf * STG + (wid + 8 * i) * 1024));
; #pragma unroll
;     for (int i = 0; i < 2; ++i) glds16(vp[i] + (size_t)t * vstr, (unsigned)__builtin_amdgcn_readfirstlane(lds0 + buf * STG + KSZ + (wid + 8 * i) * 1024));
;   };
; #pragma unroll
;   for (int i = 0; i < DPF; ++i) issue(i, i);
;   bf16x8 qf[NS];
; #pragma unroll
;   for (int i = 0; i < NS; ++i) qf[i] = *(const bf16x8*)(s.q + (size_t)(qw0 + r) * s.ldq + 16 * i + 8 * h);
.LBB0_99:
	s_xor_b64 s[10:11], s[12:13], -1
	s_lshl_b64 s[14:15], s[14:15], 1
	v_mov_b32_e32 v24, v163
	s_add_u32 s14, s22, s14
	s_addc_u32 s15, s23, s15
	v_readfirstlane_b32 s18, v24
	s_ashr_i32 s18, s18, 6
	s_lshl_b32 s45, s18, 5
	v_and_b32_e32 v0, 63, v24
	s_lshl_b32 s18, s18, 10
	v_lshl_or_b32 v8, v0, 4, s18
	v_ashrrev_i32_e32 v0, 31, v8
	v_lshrrev_b32_e32 v0, 25, v0
	v_add_u32_e32 v0, v8, v0
	v_ashrrev_i32_e32 v3, 7, v0
	v_and_b32_e32 v0, 0xffffff80, v0
	v_sub_u32_e32 v0, v8, v0
	v_ashrrev_i32_e32 v0, 4, v0
	v_bitop3_b32 v9, v0, v3, 7 bitop3:0x78
	v_lshlrev_b32_e32 v2, 3, v9
	v_mov_b64_e32 v[4:5], s[14:15]
	v_mad_i64_i32 v[6:7], s[14:15], v3, s59, v[4:5]
	v_ashrrev_i32_e32 v3, 31, v2
	v_ashrrev_i32_e32 v0, 8, v8
	v_lshl_add_u64 v[2:3], v[2:3], 1, v[6:7]
	v_lshlrev_b32_e32 v6, 2, v0
	v_and_b32_e32 v10, 3, v24
	v_xor_b32_e32 v6, v6, v24
	v_and_or_b32 v11, v6, 12, v10
	v_mul_hi_i32_i24_e32 v7, 0x1800, v0
	v_mul_i32_i24_e32 v6, 0x1800, v0
	v_lshl_add_u64 v[6:7], s[4:5], 0, v[6:7]
	v_lshlrev_b32_e32 v0, 4, v11
	v_lshl_add_u64 v[18:19], v[6:7], 0, v[0:1]
	v_add_u32_e32 v0, 0x2000, v8
	v_ashrrev_i32_e32 v0, 8, v0
	v_lshlrev_b32_e32 v6, 2, v0
	v_xor_b32_e32 v6, v6, v24
	v_and_or_b32 v8, v6, 12, v10
	v_mul_hi_i32_i24_e32 v7, 0x1800, v0
	v_mul_i32_i24_e32 v6, 0x1800, v0
	v_lshl_add_u64 v[6:7], s[4:5], 0, v[6:7]
	v_lshlrev_b32_e32 v0, 4, v8
	v_cmp_gt_i32_e32 vcc, 8, v9
	v_lshl_add_u64 v[20:21], v[6:7], 0, v[0:1]
	s_waitcnt vmcnt(0)
	s_mov_b64 s[14:15], 0x800
	v_cndmask_b32_e64 v7, -1, 0, vcc
	v_cndmask_b32_e64 v6, v200, 0, vcc
	v_lshl_add_u64 v[22:23], v[2:3], 0, v[6:7]
	v_lshl_add_u64 v[2:3], v[22:23], 0, s[14:15]
	s_add_i32 s46, s18, 0
	s_mov_b32 s14, m0
	s_mov_b32 m0, s46
	s_nop 0
	global_load_lds_dwordx4 v[2:3], off
	s_mov_b32 m0, s14
	s_add_i32 s47, s46, 0x2000
	s_mov_b32 s14, m0
	s_mov_b32 m0, s47
	s_nop 0
	global_load_lds_dwordx4 v[18:19], off
	s_mov_b32 m0, s14
	s_add_i32 s52, s46, 0x4000
	s_mov_b32 s14, m0
	s_mov_b32 m0, s52
	s_nop 0
	global_load_lds_dwordx4 v[20:21], off
	s_mov_b32 m0, s14
	s_mov_b64 s[14:15], 0x60800
	v_lshl_add_u64 v[2:3], v[22:23], 0, s[14:15]
	s_add_i32 s14, s46, 0x6000
	s_mov_b32 s15, m0
	s_mov_b32 m0, s14
	s_nop 0
	global_load_lds_dwordx4 v[2:3], off
	s_mov_b32 m0, s15
	v_lshl_add_u64 v[2:3], v[18:19], 0, s[26:27]
	s_add_i32 s14, s46, 0x8000
	s_mov_b32 s15, m0
	s_mov_b32 m0, s14
	s_nop 0
	global_load_lds_dwordx4 v[2:3], off
	s_mov_b32 m0, s15
	v_lshl_add_u64 v[2:3], v[20:21], 0, s[26:27]
	s_add_i32 s14, s46, 0xa000
	s_mov_b32 s15, m0
	s_mov_b32 m0, s14
	s_nop 0
	global_load_lds_dwordx4 v[2:3], off
	s_mov_b32 m0, s15
	s_mov_b64 s[14:15], 0xc0800
	v_lshl_add_u64 v[2:3], v[22:23], 0, s[14:15]
	s_add_i32 s14, s46, 0xc000
	v_and_b32_e32 v25, 31, v24
	s_add_i32 s45, s45, s40
	s_mov_b32 s15, m0
	s_mov_b32 m0, s14
	s_nop 0
	global_load_lds_dwordx4 v[2:3], off
	s_mov_b32 m0, s15
	v_lshl_add_u64 v[2:3], v[18:19], 0, s[28:29]
	s_add_i32 s14, s46, 0xe000
	v_bfe_u32 v26, v24, 5, 1
	s_mov_b32 s15, m0
	s_mov_b32 m0, s14
	s_nop 0
	global_load_lds_dwordx4 v[2:3], off
	s_mov_b32 m0, s15
	v_lshl_add_u64 v[2:3], v[20:21], 0, s[28:29]
	s_add_i32 s14, s46, 0x10000
	v_or_b32_e32 v212, s45, v25
	s_mov_b32 s15, m0
	s_mov_b32 m0, s14
	s_nop 0
	global_load_lds_dwordx4 v[2:3], off
	s_mov_b32 m0, s15
	v_lshlrev_b32_e32 v0, 4, v26
	v_mad_i64_i32 v[2:3], s[14:15], v212, s59, v[4:5]
	v_lshl_add_u64 v[14:15], v[2:3], 0, v[0:1]
	global_load_dwordx4 v[2:5], v[14:15], off
	global_load_dwordx4 v[6:9], v[14:15], off offset:32
	global_load_dwordx4 v[10:13], v[14:15], off offset:64
	s_nop 0
	global_load_dwordx4 v[14:17], v[14:15], off offset:96
	s_mov_b64 s[14:15], 0x120800
	v_lshlrev_b32_e32 v213, 7, v25
	v_lshlrev_b32_e32 v214, 10, v26
	v_lshlrev_b32_e32 v223, 2, v26
	v_lshl_add_u64 v[166:167], v[20:21], 0, s[30:31]
	v_lshl_add_u64 v[168:169], v[18:19], 0, s[30:31]
	v_lshl_add_u64 v[170:171], v[22:23], 0, s[14:15]
	s_mov_b32 s53, 63
	s_mov_b32 s54, 3
	s_mov_b32 s55, 0
	s_or_b32 s56, s45, 31
	v_mov_b32_e32 v227, 0
	s_mov_b32 s57, s44
	s_mov_b64 s[14:15], 0
	s_mov_b32 s58, 3
	s_waitcnt vmcnt(3)
	s_nop 0
	v_lshlrev_b32_e32 v0, 16, v2
	v_and_b32_e32 v2, 0xffff0000, v2
	v_mul_f32_e32 v2, 0x3e38aa3b, v2
	s_waitcnt vmcnt(2)
	s_waitcnt vmcnt(1)
	s_waitcnt vmcnt(0)
; DI unsigned cvt_pk_bf16(float lo, float hi) { unsigned r; asm volatile("v_cvt_pk_bf16_f32 %0, %1, %2" : "=v"(r) : "v"(lo), "v"(hi)); return r; }
; DI float bf_lo(unsigned w) { return __uint_as_float(w << 16); }
; DI float bf_hi(unsigned w) { return __uint_as_float(w & 0xffff0000u); }
; template <int DK>
; DI void attn_pass(const AttnSrc& s, const int q0, const float sc, LAS unsigned char* lds, f32x16 (&O)[4]) {
;     ...
;   if (REL) {
; #pragma unroll
;   for (int i = 0; i < NS; ++i) {
;     const u32x4 w = __builtin_bit_cast(u32x4, qf[i]); u32x4 o;
;     o.x = cvt_pk_bf16(bf_lo(w.x) * sc, bf_hi(w.x) * sc); o.y = cvt_pk_bf16(bf_lo(w.y) * sc, bf_hi(w.y) * sc);
;     o.z = cvt_pk_bf16(bf_lo(w.z) * sc, bf_hi(w.z) * sc); o.w = cvt_pk_bf16(bf_lo(w.w) * sc, bf_hi(w.w) * sc);
;     qf[i] = __builtin_bit_cast(bf16x8, o);
;   }
;   }
;   f32x16 negm;
; #pragma unroll
;   for (int j = 0; j < 16; ++j) negm[j] = 0.f;
;   if (REL) asm volatile("" : "+v"(negm));
;   const int kx = (DK == 64) ? (r & 7) : ((r >> 1) & 7);
;   const int krow = r * ROWB;
;   const int i15 = lane & 15;
;   const int vrow = (4 * h + (i15 >> 2)) * 256 + ((lane >> 4) & 1) * 32 + (lane & 3) * 8;
;   const int vx = (i15 >> 2) & 3;
;   int buf = 0, pbuf = DPF;
;     ...
;     buf = (buf + 1 == NBUF) ? 0 : buf + 1; pbuf = (pbuf + 1 == NBUF) ? 0 : pbuf + 1;
	v_lshlrev_b32_e32 v29, 16, v5
	v_mul_f32_e32 v0, 0x3e38aa3b, v0
	v_cvt_pk_bf16_f32 v128, v0, v2
	v_and_b32_e32 v2, 0xffff0000, v5
	v_lshlrev_b32_e32 v27, 16, v3
	v_and_b32_e32 v3, 0xffff0000, v3
	v_lshlrev_b32_e32 v28, 16, v4
	v_and_b32_e32 v4, 0xffff0000, v4
	v_mul_f32_e32 v0, 0x3e38aa3b, v29
	v_mul_f32_e32 v2, 0x3e38aa3b, v2
	v_mul_f32_e32 v27, 0x3e38aa3b, v27
	v_mul_f32_e32 v3, 0x3e38aa3b, v3
	v_mul_f32_e32 v28, 0x3e38aa3b, v28
	v_mul_f32_e32 v4, 0x3e38aa3b, v4
	v_cvt_pk_bf16_f32 v129, v27, v3
	v_cvt_pk_bf16_f32 v130, v28, v4
	v_cvt_pk_bf16_f32 v131, v0, v2
	v_lshlrev_b32_e32 v0, 16, v6
	v_and_b32_e32 v2, 0xffff0000, v6
	v_mul_f32_e32 v0, 0x3e38aa3b, v0
	v_mul_f32_e32 v2, 0x3e38aa3b, v2
	v_cvt_pk_bf16_f32 v132, v0, v2
	v_lshlrev_b32_e32 v0, 16, v7
	v_and_b32_e32 v2, 0xffff0000, v7
	v_mul_f32_e32 v0, 0x3e38aa3b, v0
	v_mul_f32_e32 v2, 0x3e38aa3b, v2
	v_cvt_pk_bf16_f32 v133, v0, v2
	v_lshlrev_b32_e32 v0, 16, v8
	v_and_b32_e32 v2, 0xffff0000, v8
	v_mul_f32_e32 v0, 0x3e38aa3b, v0
	v_mul_f32_e32 v2, 0x3e38aa3b, v2
	v_cvt_pk_bf16_f32 v134, v0, v2
	v_lshlrev_b32_e32 v0, 16, v9
	v_and_b32_e32 v2, 0xffff0000, v9
	v_mul_f32_e32 v0, 0x3e38aa3b, v0
	v_mul_f32_e32 v2, 0x3e38aa3b, v2
	v_cvt_pk_bf16_f32 v135, v0, v2
	v_lshlrev_b32_e32 v0, 16, v10
	v_and_b32_e32 v2, 0xffff0000, v10
	v_mul_f32_e32 v0, 0x3e38aa3b, v0
	v_mul_f32_e32 v2, 0x3e38aa3b, v2
	v_cvt_pk_bf16_f32 v136, v0, v2
	v_lshlrev_b32_e32 v0, 16, v11
	v_and_b32_e32 v2, 0xffff0000, v11
	v_mul_f32_e32 v0, 0x3e38aa3b, v0
	v_mul_f32_e32 v2, 0x3e38aa3b, v2
	v_cvt_pk_bf16_f32 v137, v0, v2
	v_lshlrev_b32_e32 v0, 16, v12
	v_and_b32_e32 v2, 0xffff0000, v12
	v_mul_f32_e32 v0, 0x3e38aa3b, v0
	v_mul_f32_e32 v2, 0x3e38aa3b, v2
	v_cvt_pk_bf16_f32 v138, v0, v2
	v_lshlrev_b32_e32 v0, 16, v13
	v_and_b32_e32 v2, 0xffff0000, v13
	v_mul_f32_e32 v0, 0x3e38aa3b, v0
	v_mul_f32_e32 v2, 0x3e38aa3b, v2
	v_cvt_pk_bf16_f32 v139, v0, v2
	v_lshlrev_b32_e32 v0, 16, v14
	v_and_b32_e32 v2, 0xffff0000, v14
	v_mul_f32_e32 v0, 0x3e38aa3b, v0
	v_mul_f32_e32 v2, 0x3e38aa3b, v2
	v_cvt_pk_bf16_f32 v140, v0, v2
	v_lshlrev_b32_e32 v0, 16, v15
	v_and_b32_e32 v2, 0xffff0000, v15
	v_mul_f32_e32 v0, 0x3e38aa3b, v0
	v_mul_f32_e32 v2, 0x3e38aa3b, v2
	v_cvt_pk_bf16_f32 v141, v0, v2
	v_lshlrev_b32_e32 v0, 16, v16
	v_and_b32_e32 v2, 0xffff0000, v16
	v_mul_f32_e32 v0, 0x3e38aa3b, v0
	v_mul_f32_e32 v2, 0x3e38aa3b, v2
	v_cvt_pk_bf16_f32 v142, v0, v2
	v_lshlrev_b32_e32 v0, 16, v17
	v_and_b32_e32 v2, 0xffff0000, v17
	v_lshlrev_b32_e32 v17, 1, v24
	v_and_b32_e32 v216, 32, v17
	v_lshlrev_b32_e32 v17, 3, v24
	v_bfe_u32 v16, v24, 2, 2
	v_and_b32_e32 v217, 24, v17
	v_and_b32_e32 v17, 7, v24
	v_bitop3_b32 v24, v26, v24, 7 bitop3:0x78
	v_lshlrev_b32_e32 v218, 4, v24
	v_bitop3_b32 v24, v26, v17, 2 bitop3:0x36
	v_mul_f32_e32 v0, 0x3e38aa3b, v0
	v_mul_f32_e32 v2, 0x3e38aa3b, v2
	v_mov_b32_e32 v14, v1
	v_mov_b32_e32 v15, v1
	v_lshlrev_b32_e32 v219, 4, v24
	v_bitop3_b32 v24, v26, v17, 4 bitop3:0x36
	v_bitop3_b32 v17, v26, v17, 6 bitop3:0x36
	v_cvt_pk_bf16_f32 v143, v0, v2
	v_mov_b32_e32 v0, v1
	v_mov_b32_e32 v2, v1
	v_mov_b32_e32 v3, v1
	v_mov_b32_e32 v4, v1
	v_mov_b32_e32 v5, v1
	v_mov_b32_e32 v6, v1
	v_mov_b32_e32 v7, v1
	v_mov_b32_e32 v8, v1
	v_mov_b32_e32 v9, v1
	v_mov_b32_e32 v10, v1
	v_mov_b32_e32 v11, v1
	v_mov_b32_e32 v12, v1
	v_mov_b32_e32 v13, v1
	v_mov_b64_e32 v[94:95], v[14:15]
	v_lshlrev_b32_e32 v215, 8, v16
	v_lshlrev_b32_e32 v220, 4, v24
	v_lshlrev_b32_e32 v221, 4, v17
	v_lshlrev_b32_e32 v222, 6, v16
	v_mov_b64_e32 v[30:31], v[14:15]
	v_mov_b64_e32 v[46:47], v[14:15]
	v_mov_b64_e32 v[62:63], v[14:15]
	v_mov_b64_e32 v[78:79], v[14:15]
	v_mov_b64_e32 v[92:93], v[12:13]
	v_mov_b64_e32 v[90:91], v[10:11]
	v_mov_b64_e32 v[88:89], v[8:9]
	v_mov_b64_e32 v[86:87], v[6:7]
	v_mov_b64_e32 v[84:85], v[4:5]
	v_mov_b64_e32 v[82:83], v[2:3]
	v_mov_b64_e32 v[80:81], v[0:1]
	v_xor_b32_e32 v224, 64, v222
	v_xor_b32_e32 v225, 0x80, v222
	v_xor_b32_e32 v226, 0xc0, v222
	v_mov_b64_e32 v[28:29], v[12:13]
	v_mov_b64_e32 v[26:27], v[10:11]
	v_mov_b64_e32 v[24:25], v[8:9]
	v_mov_b64_e32 v[22:23], v[6:7]
	v_mov_b64_e32 v[20:21], v[4:5]
	v_mov_b64_e32 v[18:19], v[2:3]
	v_mov_b64_e32 v[16:17], v[0:1]
	v_mov_b64_e32 v[44:45], v[12:13]
	v_mov_b64_e32 v[42:43], v[10:11]
	v_mov_b64_e32 v[40:41], v[8:9]
	v_mov_b64_e32 v[38:39], v[6:7]
	v_mov_b64_e32 v[36:37], v[4:5]
	v_mov_b64_e32 v[34:35], v[2:3]
	v_mov_b64_e32 v[32:33], v[0:1]
	v_mov_b64_e32 v[60:61], v[12:13]
	v_mov_b64_e32 v[58:59], v[10:11]
	v_mov_b64_e32 v[56:57], v[8:9]
	v_mov_b64_e32 v[54:55], v[6:7]
	v_mov_b64_e32 v[52:53], v[4:5]
	v_mov_b64_e32 v[50:51], v[2:3]
	v_mov_b64_e32 v[48:49], v[0:1]
	v_mov_b64_e32 v[76:77], v[12:13]
	v_mov_b64_e32 v[74:75], v[10:11]
	v_mov_b64_e32 v[72:73], v[8:9]
	v_mov_b64_e32 v[70:71], v[6:7]
	v_mov_b64_e32 v[68:69], v[4:5]
	v_mov_b64_e32 v[66:67], v[2:3]
	v_mov_b64_e32 v[64:65], v[0:1]
	v_mov_b32_e32 v14, 0
	s_branch .LBB0_102
.LBB0_101:
	s_add_i32 s18, s55, 1
	s_cmp_lg_u32 s18, 4
	s_cselect_b32 s55, s18, 0
	s_add_i32 s18, s58, 1
	s_cmp_lg_u32 s18, 4
	s_cselect_b32 s58, s18, 0
	s_add_u32 s14, s14, 0x60000
	s_addc_u32 s15, s15, 0
	s_add_i32 s53, s53, 64
	s_add_i32 s54, s54, 1
	s_add_i32 s57, s57, -1
	s_cmp_lg_u32 s42, s14
	s_cbranch_scc0 .LBB0_117

; template <int DK>
; DI void attn_pass(const AttnSrc& s, const int q0, const float sc, LAS unsigned char* lds, f32x16 (&O)[4]) {
;     ...
;     if (t + DPF < NT) issue(t + DPF, pbuf);
;     if (64 * t <= qw0 + 31) {
;       LAS unsigned char* Kb = lds + buf * STG; LAS unsigned char* Vb = lds + buf * STG + KSZ;
;       f32x16 p0, p1;
;       constexpr int GS = (DK == 64) ? 4 : 2, NG = NS / GS;
;       bf16x8 kfa[2][GS], kfb[2][GS];
;       auto kload = [&](int g, int slot) {
; #pragma unroll
;         for (int j = 0; j < GS; ++j) { const int lc = 2 * (g * GS + j) + h; const int ph = (DK == 64) ? (lc ^ kx) : ((lc & ~7) | ((lc & 7) ^ kx));
;           kfa[slot][j] = *(const LAS bf16x8*)(Kb + krow + ph * 16); kfb[slot][j] = *(const LAS bf16x8*)(Kb + krow + 32 * ROWB + ph * 16); }
;       };
;       kload(0, 0);
; #pragma unroll
;       for (int g = 0; g < NG; ++g) {
;         if (g + 1 < NG) kload(g + 1, (g + 1) & 1);
;         __builtin_amdgcn_s_setprio(1);
; #pragma unroll
;         for (int j = 0; j < GS; ++j) {
;           if (g == 0 && j == 0) {
;             if (REL) {
;               p0 = __builtin_amdgcn_mfma_f32_32x32x16_bf16(kfa[0][0], qf[0], negm, 0, 0, 0);
;               p1 = __builtin_amdgcn_mfma_f32_32x32x16_bf16(kfb[0][0], qf[0], negm, 0, 0, 0);
;             } else {
;               f32x16 z;
; #pragma unroll
;               for (int jj = 0; jj < 16; ++jj) z[jj] = 0.f;
;               p0 = __builtin_amdgcn_mfma_f32_32x32x16_bf16(kfa[0][0], qf[0], z, 0, 0, 0);
;               p1 = __builtin_amdgcn_mfma_f32_32x32x16_bf16(kfb[0][0], qf[0], z, 0, 0, 0);
;             }
;           } else {
;             p0 = __builtin_amdgcn_mfma_f32_32x32x16_bf16(kfa[g & 1][j], qf[g * GS + j], p0, 0, 0, 0);
;             p1 = __builtin_amdgcn_mfma_f32_32x32x16_bf16(kfb[g & 1][j], qf[g * GS + j], p1, 0, 0, 0);
;           }
;         }
;         __builtin_amdgcn_s_setprio(0);
;       }
;       bf16x8 vf[2][4];
;       auto vload = [&](int vt, int slot) {
;         const int vcol = vrow + ((vt ^ vx) << 6);
; #pragma unroll
;         for (int ks = 0; ks < 4; ++ks) {
;           const s16x4 lo = __builtin_bit_cast(s16x4, __builtin_amdgcn_ds_read_tr16_b64_v4i16((LAS s16x4*)(Vb + vcol + ks * 16 * 256)));
;           const s16x4 hi = __builtin_bit_cast(s16x4, __builtin_amdgcn_ds_read_tr16_b64_v4i16((LAS s16x4*)(Vb + vcol + (ks * 16 + 8) * 256)));
.LBB0_112:
	s_sub_i32 s18, s53, 63
	s_cmp_gt_i32 s18, s56
	s_cbranch_scc1 .Ln64_skip
	s_mul_i32 s18, s55, 0x6000
	s_add_i32 s18, s18, 0
	v_add_u32_e32 v0, s18, v213
	v_add_u32_e32 v6, v0, v218
	v_add_u32_e32 v15, v0, v219
	ds_read_b128 v[2:5], v6
	ds_read_b128 v[6:9], v6 offset:4096
	ds_read_b128 v[10:13], v15
	ds_read_b128 v[144:147], v15 offset:4096
	v_add_u32_e32 v15, v0, v220
	v_add_u32_e32 v0, v0, v221
	ds_read_b128 v[230:233], v15
	ds_read_b128 v[234:237], v15 offset:4096
	ds_read_b128 v[238:241], v0
	ds_read_b128 v[242:245], v0 offset:4096
	s_setprio 1
	s_waitcnt lgkmcnt(6)
	v_mfma_f32_32x32x16_bf16 v[112:127], v[2:5], v[128:131], v[80:95]
	v_mfma_f32_32x32x16_bf16 v[96:111], v[6:9], v[128:131], v[80:95]
	s_waitcnt lgkmcnt(4)
	v_mfma_f32_32x32x16_bf16 v[112:127], v[10:13], v[132:135], v[112:127]
	v_mfma_f32_32x32x16_bf16 v[96:111], v[144:147], v[132:135], v[96:111]
	s_waitcnt lgkmcnt(2)
	v_mfma_f32_32x32x16_bf16 v[112:127], v[230:233], v[136:139], v[112:127]
	v_mfma_f32_32x32x16_bf16 v[96:111], v[234:237], v[136:139], v[96:111]
	s_waitcnt lgkmcnt(0)
	v_mfma_f32_32x32x16_bf16 v[112:127], v[238:241], v[140:143], v[112:127]
	v_mfma_f32_32x32x16_bf16 v[96:111], v[242:245], v[140:143], v[96:111]
	s_setprio 0
	v_add3_u32 v0, s18, v214, v215
	v_add3_u32 v15, v0, v216, v217
	v_add_u32_e32 v246, v15, v222
	v_add_u32_e32 v247, v15, v224
	v_add_u32_e32 v248, v15, v225
	v_add_u32_e32 v249, v15, v226
	s_cmp_ge_u32 s54, s41
	s_cbranch_scc1 .Ln64_dmadone
	s_mul_i32 s18, s58, 0x6000
	v_lshl_add_u64 v[2:3], v[170:171], 0, s[14:15]
	s_add_i32 s19, s18, s46
	s_mov_b32 s62, m0
	s_mov_b32 m0, s19
	s_nop 0
	global_load_lds_dwordx4 v[2:3], off
	s_mov_b32 m0, s62
	v_lshl_add_u64 v[2:3], v[168:169], 0, s[14:15]
	s_add_i32 s19, s18, s47
	s_mov_b32 s62, m0
	s_mov_b32 m0, s19
	s_nop 0
	global_load_lds_dwordx4 v[2:3], off
	s_mov_b32 m0, s62
	v_lshl_add_u64 v[2:3], v[166:167], 0, s[14:15]
	s_add_i32 s18, s18, s52
	s_mov_b32 s19, m0
	s_mov_b32 m0, s18
	s_nop 0
	global_load_lds_dwordx4 v[2:3], off
	s_mov_b32 m0, s19
.Ln64_dmadone:
	ds_read_b64_tr_b16 v[2:3], v246 offset:8192
	ds_read_b64_tr_b16 v[4:5], v246 offset:10240
	ds_read_b64_tr_b16 v[6:7], v247 offset:8192
	ds_read_b64_tr_b16 v[8:9], v247 offset:10240
	ds_read_b64_tr_b16 v[10:11], v248 offset:8192
	ds_read_b64_tr_b16 v[12:13], v248 offset:10240
	ds_read_b64_tr_b16 v[144:145], v249 offset:8192
	ds_read_b64_tr_b16 v[146:147], v249 offset:10240
	s_cmp_le_i32 s53, s45
	s_cbranch_scc1 .Ln64_nomask
	v_add_u32_e32 v0, s53, v223
	v_subrev_u32_e32 v231, 31, v0
	v_subrev_u32_e32 v230, 63, v0
	v_cmp_le_i32_e32 vcc, v231, v212
	s_nop 1
	v_cndmask_b32_e32 v96, v201, v96, vcc
	v_cmp_lt_i32_e32 vcc, v230, v212
	s_nop 1
	v_cndmask_b32_e32 v113, v201, v113, vcc
	v_cmp_le_i32_e32 vcc, v230, v212
	v_subrev_u32_e32 v230, 30, v0
	s_nop 0
	v_cndmask_b32_e32 v112, v201, v112, vcc
	v_cmp_le_i32_e32 vcc, v230, v212
	v_subrev_u32_e32 v230, 61, v0
	s_nop 0
	v_cndmask_b32_e32 v97, v201, v97, vcc
	v_cmp_le_i32_e32 vcc, v230, v212
	v_subrev_u32_e32 v230, 29, v0
	s_nop 0
	v_cndmask_b32_e32 v114, v201, v114, vcc
	v_cmp_le_i32_e32 vcc, v230, v212
	v_subrev_u32_e32 v230, 60, v0
	s_nop 0
	v_cndmask_b32_e32 v98, v201, v98, vcc
	v_cmp_le_i32_e32 vcc, v230, v212
	v_subrev_u32_e32 v230, 28, v0
	s_nop 0
	v_cndmask_b32_e32 v115, v201, v115, vcc
	v_cmp_le_i32_e32 vcc, v230, v212
	v_subrev_u32_e32 v230, 55, v0
	s_nop 0
	v_cndmask_b32_e32 v99, v201, v99, vcc
	v_cmp_le_i32_e32 vcc, v230, v212
	v_subrev_u32_e32 v230, 23, v0
	s_nop 0
	v_cndmask_b32_e32 v116, v201, v116, vcc
	v_cmp_le_i32_e32 vcc, v230, v212
	v_subrev_u32_e32 v230, 54, v0
	s_nop 0
	v_cndmask_b32_e32 v100, v201, v100, vcc
	v_cmp_le_i32_e32 vcc, v230, v212
	v_subrev_u32_e32 v230, 22, v0
	s_nop 0
	v_cndmask_b32_e32 v117, v201, v117, vcc
	v_cmp_le_i32_e32 vcc, v230, v212
	v_subrev_u32_e32 v230, 53, v0
	s_nop 0
	v_cndmask_b32_e32 v101, v201, v101, vcc
	v_cmp_le_i32_e32 vcc, v230, v212
	v_subrev_u32_e32 v230, 21, v0
	s_nop 0
	v_cndmask_b32_e32 v118, v201, v118, vcc
	v_cmp_le_i32_e32 vcc, v230, v212
	v_subrev_u32_e32 v230, 52, v0
	s_nop 0
	v_cndmask_b32_e32 v102, v201, v102, vcc
	v_cmp_le_i32_e32 vcc, v230, v212
	v_subrev_u32_e32 v230, 20, v0
	s_nop 0
	v_cndmask_b32_e32 v119, v201, v119, vcc
	v_cmp_le_i32_e32 vcc, v230, v212
	v_subrev_u32_e32 v230, 47, v0
	s_nop 0
	v_cndmask_b32_e32 v103, v201, v103, vcc
	v_cmp_le_i32_e32 vcc, v230, v212
	v_add_u32_e32 v230, -15, v0
	s_nop 0
	v_cndmask_b32_e32 v120, v201, v120, vcc
	v_cmp_le_i32_e32 vcc, v230, v212
	v_subrev_u32_e32 v230, 46, v0
	s_nop 0
	v_cndmask_b32_e32 v104, v201, v104, vcc
	v_cmp_le_i32_e32 vcc, v230, v212
	v_add_u32_e32 v230, -14, v0
	s_nop 0
	v_cndmask_b32_e32 v121, v201, v121, vcc
	v_cmp_le_i32_e32 vcc, v230, v212
	v_subrev_u32_e32 v230, 45, v0
	s_nop 0
	v_cndmask_b32_e32 v105, v201, v105, vcc
	v_cmp_le_i32_e32 vcc, v230, v212
	v_add_u32_e32 v230, -13, v0
	s_nop 0
	v_cndmask_b32_e32 v122, v201, v122, vcc
	v_cmp_le_i32_e32 vcc, v230, v212
	v_subrev_u32_e32 v230, 44, v0
	s_nop 0
	v_cndmask_b32_e32 v106, v201, v106, vcc
	v_cmp_le_i32_e32 vcc, v230, v212
	v_add_u32_e32 v230, -12, v0
	s_nop 0
	v_cndmask_b32_e32 v123, v201, v123, vcc
	v_cmp_le_i32_e32 vcc, v230, v212
	v_subrev_u32_e32 v230, 39, v0
	s_nop 0
	v_cndmask_b32_e32 v107, v201, v107, vcc
	v_cmp_le_i32_e32 vcc, v230, v212
	v_add_u32_e32 v230, -7, v0
	s_nop 0
	v_cndmask_b32_e32 v124, v201, v124, vcc
	v_cmp_le_i32_e32 vcc, v230, v212
	v_subrev_u32_e32 v230, 38, v0
	s_nop 0
	v_cndmask_b32_e32 v108, v201, v108, vcc
	v_cmp_le_i32_e32 vcc, v230, v212
	v_add_u32_e32 v230, -6, v0
	s_nop 0
	v_cndmask_b32_e32 v125, v201, v125, vcc
	v_cmp_le_i32_e32 vcc, v230, v212
	v_subrev_u32_e32 v230, 37, v0
	s_nop 0
	v_cndmask_b32_e32 v109, v201, v109, vcc
	v_cmp_le_i32_e32 vcc, v230, v212
	v_add_u32_e32 v230, -5, v0
	s_nop 0
	v_cndmask_b32_e32 v126, v201, v126, vcc
	v_cmp_le_i32_e32 vcc, v230, v212
	v_subrev_u32_e32 v230, 36, v0
	v_add_u32_e32 v0, -4, v0
	v_cndmask_b32_e32 v110, v201, v110, vcc
	v_cmp_le_i32_e32 vcc, v230, v212
	s_nop 1
	v_cndmask_b32_e32 v127, v201, v127, vcc
	v_cmp_le_i32_e32 vcc, v0, v212
	s_nop 1
	v_cndmask_b32_e32 v111, v201, v111, vcc
; DI float max3f(float a, float b, float c) { float r; asm("v_max3_f32 %0, %1, %2, %3" : "=v"(r) : "v"(a), "v"(b), "v"(c)); return r; }
; template <int DK>
; DI void attn_pass(const AttnSrc& s, const int q0, const float sc, LAS unsigned char* lds, f32x16 (&O)[4]) {
;     ...
;       asm volatile("s_nop 15\n\ts_nop 7" : "+v"(p0), "+v"(p1));
;       float mx;
;       { float ma = max3f(p0[0], p0[1], p1[0]), mb = max3f(p0[2], p0[3], p1[1]); ma = max3f(ma, p1[2], p1[3]);
; #pragma unroll
;         for (int j = 4; j < 16; j += 4) { ma = max3f(ma, p0[j], p0[j + 1]); mb = max3f(mb, p0[j + 2], p0[j + 3]); ma = max3f(ma, p1[j], p1[j + 1]); mb = max3f(mb, p1[j + 2], p1[j + 3]); }
;         mx = fmaxf(ma, mb); }
;       { auto rr = __builtin_amdgcn_permlane32_swap(__float_as_uint(mx), __float_as_uint(mx), false, false); mx = fmaxf(__uint_as_float(rr[0]), __uint_as_float(rr[1])); }
;       float rs = 0.f;
;       if (REL) {
;         const bool grow = (mx > 8.f) || (t == 0);
;         if (__builtin_amdgcn_ballot_w64(grow) != 0ull) {
;           const float dl = grow ? mx : 0.f;
;           const float alpha = __builtin_amdgcn_exp2f(-dl);
;           mrun += dl; lrun *= alpha;
; #pragma unroll
;           for (int j = 0; j < 16; ++j) { p0[j] -= dl; p1[j] -= dl; negm[j] = -mrun; }
;           asm volatile("" : "+v"(negm));
; #pragma unroll
;           for (int i = 0; i < 4; ++i)
; #pragma unroll
;             for (int j = 0; j < 16; ++j) O[i][j] *= alpha;
;         }
.Ln64_nomask:
	s_mov_b32 s18, 0x41000000
	v_max3_f32 v0, v112, v113, v96
	v_max3_f32 v230, v114, v115, v97
	s_cmp_eq_u32 s53, 63
	v_max3_f32 v0, v0, v98, v99
	v_max3_f32 v230, v230, v118, v119
	s_nop 0
	v_max3_f32 v0, v0, v116, v117
	v_max3_f32 v230, v230, v102, v103
	s_nop 0
	v_max3_f32 v0, v0, v100, v101
	v_max3_f32 v230, v230, v122, v123
	s_nop 0
	v_max3_f32 v0, v0, v120, v121
	v_max3_f32 v230, v230, v106, v107
	s_nop 0
	v_max3_f32 v0, v0, v104, v105
	v_max3_f32 v230, v230, v126, v127
	s_nop 0
	v_max3_f32 v0, v0, v124, v125
	v_max3_f32 v230, v230, v110, v111
	s_nop 0
	v_max3_f32 v0, v0, v108, v109
	v_max_f32_e32 v230, v230, v230
	v_max_f32_e32 v0, v0, v0
	v_max_f32_e32 v0, v0, v230
	v_mov_b32_e32 v230, v0
	s_nop 1
	v_permlane32_swap_b32_e32 v0, v230
	v_max_f32_e32 v230, v230, v230
	v_max_f32_e32 v0, v0, v0
	v_max_f32_e32 v0, v0, v230
	v_cmp_lt_f32_e32 vcc, s18, v0
	s_cselect_b64 s[18:19], -1, 0
	s_or_b64 vcc, s[18:19], vcc
	s_cbranch_vccz .Ln64_exp
	v_cndmask_b32_e32 v0, 0, v0, vcc
	v_add_f32_e32 v227, v227, v0
	v_pk_add_f32 v[112:113], v[112:113], v[0:1] op_sel_hi:[1,0] neg_lo:[0,1] neg_hi:[0,1]
	v_pk_add_f32 v[96:97], v[96:97], v[0:1] op_sel_hi:[1,0] neg_lo:[0,1] neg_hi:[0,1]
	v_pk_add_f32 v[114:115], v[114:115], v[0:1] op_sel_hi:[1,0] neg_lo:[0,1] neg_hi:[0,1]
	v_pk_add_f32 v[98:99], v[98:99], v[0:1] op_sel_hi:[1,0] neg_lo:[0,1] neg_hi:[0,1]
	v_pk_add_f32 v[116:117], v[116:117], v[0:1] op_sel_hi:[1,0] neg_lo:[0,1] neg_hi:[0,1]
	v_pk_add_f32 v[100:101], v[100:101], v[0:1] op_sel_hi:[1,0] neg_lo:[0,1] neg_hi:[0,1]
	v_pk_add_f32 v[118:119], v[118:119], v[0:1] op_sel_hi:[1,0] neg_lo:[0,1] neg_hi:[0,1]
	v_pk_add_f32 v[102:103], v[102:103], v[0:1] op_sel_hi:[1,0] neg_lo:[0,1] neg_hi:[0,1]
	v_pk_add_f32 v[120:121], v[120:121], v[0:1] op_sel_hi:[1,0] neg_lo:[0,1] neg_hi:[0,1]
	v_pk_add_f32 v[104:105], v[104:105], v[0:1] op_sel_hi:[1,0] neg_lo:[0,1] neg_hi:[0,1]
	v_pk_add_f32 v[122:123], v[122:123], v[0:1] op_sel_hi:[1,0] neg_lo:[0,1] neg_hi:[0,1]
	v_pk_add_f32 v[106:107], v[106:107], v[0:1] op_sel_hi:[1,0] neg_lo:[0,1] neg_hi:[0,1]
	v_pk_add_f32 v[124:125], v[124:125], v[0:1] op_sel_hi:[1,0] neg_lo:[0,1] neg_hi:[0,1]
	v_pk_add_f32 v[108:109], v[108:109], v[0:1] op_sel_hi:[1,0] neg_lo:[0,1] neg_hi:[0,1]
	v_pk_add_f32 v[126:127], v[126:127], v[0:1] op_sel_hi:[1,0] neg_lo:[0,1] neg_hi:[0,1]
	v_pk_add_f32 v[110:111], v[110:111], v[0:1] op_sel_hi:[1,0] neg_lo:[0,1] neg_hi:[0,1]
	v_exp_f32_e64 v0, -v0
	v_xor_b32_e32 v80, 0x80000000, v227
	v_mov_b32_e32 v81, v80
	v_mov_b32_e32 v82, v80
	v_mov_b32_e32 v83, v80
	v_mov_b32_e32 v84, v80
	v_mov_b32_e32 v85, v80
	v_mov_b32_e32 v86, v80
	v_mov_b32_e32 v87, v80
	v_mov_b32_e32 v88, v80
	v_mov_b32_e32 v89, v80
	v_mov_b32_e32 v90, v80
	v_mov_b32_e32 v91, v80
	v_mov_b32_e32 v92, v80
	v_mov_b32_e32 v93, v80
	v_mov_b32_e32 v94, v80
	v_mov_b32_e32 v95, v80
	v_pk_mul_f32 v[78:79], v[78:79], v[0:1] op_sel_hi:[1,0]
	v_pk_mul_f32 v[76:77], v[76:77], v[0:1] op_sel_hi:[1,0]
	v_pk_mul_f32 v[74:75], v[74:75], v[0:1] op_sel_hi:[1,0]
	v_pk_mul_f32 v[72:73], v[72:73], v[0:1] op_sel_hi:[1,0]
	v_pk_mul_f32 v[70:71], v[70:71], v[0:1] op_sel_hi:[1,0]
	v_pk_mul_f32 v[68:69], v[68:69], v[0:1] op_sel_hi:[1,0]
	v_pk_mul_f32 v[66:67], v[66:67], v[0:1] op_sel_hi:[1,0]
	v_pk_mul_f32 v[64:65], v[64:65], v[0:1] op_sel_hi:[1,0]
	v_pk_mul_f32 v[62:63], v[62:63], v[0:1] op_sel_hi:[1,0]
	v_pk_mul_f32 v[60:61], v[60:61], v[0:1] op_sel_hi:[1,0]
	v_pk_mul_f32 v[58:59], v[58:59], v[0:1] op_sel_hi:[1,0]
	v_pk_mul_f32 v[56:57], v[56:57], v[0:1] op_sel_hi:[1,0]
	v_pk_mul_f32 v[54:55], v[54:55], v[0:1] op_sel_hi:[1,0]
	v_pk_mul_f32 v[52:53], v[52:53], v[0:1] op_sel_hi:[1,0]
	v_pk_mul_f32 v[50:51], v[50:51], v[0:1] op_sel_hi:[1,0]
	v_pk_mul_f32 v[48:49], v[48:49], v[0:1] op_sel_hi:[1,0]
	v_pk_mul_f32 v[46:47], v[46:47], v[0:1] op_sel_hi:[1,0]
	v_pk_mul_f32 v[44:45], v[44:45], v[0:1] op_sel_hi:[1,0]
	v_pk_mul_f32 v[42:43], v[42:43], v[0:1] op_sel_hi:[1,0]
	v_pk_mul_f32 v[40:41], v[40:41], v[0:1] op_sel_hi:[1,0]
	v_pk_mul_f32 v[38:39], v[38:39], v[0:1] op_sel_hi:[1,0]
	v_pk_mul_f32 v[36:37], v[36:37], v[0:1] op_sel_hi:[1,0]
	v_pk_mul_f32 v[34:35], v[34:35], v[0:1] op_sel_hi:[1,0]
	v_pk_mul_f32 v[32:33], v[32:33], v[0:1] op_sel_hi:[1,0]
	v_pk_mul_f32 v[30:31], v[30:31], v[0:1] op_sel_hi:[1,0]
	v_pk_mul_f32 v[28:29], v[28:29], v[0:1] op_sel_hi:[1,0]
	v_pk_mul_f32 v[26:27], v[26:27], v[0:1] op_sel_hi:[1,0]
	v_pk_mul_f32 v[24:25], v[24:25], v[0:1] op_sel_hi:[1,0]
	v_pk_mul_f32 v[22:23], v[22:23], v[0:1] op_sel_hi:[1,0]
	v_pk_mul_f32 v[20:21], v[20:21], v[0:1] op_sel_hi:[1,0]
	v_pk_mul_f32 v[18:19], v[18:19], v[0:1] op_sel_hi:[1,0]
	v_pk_mul_f32 v[16:17], v[16:17], v[0:1] op_sel_hi:[1,0]
	v_mul_f32_e32 v14, v14, v0
; DI unsigned cvt_pk_bf16(float lo, float hi) { unsigned r; asm volatile("v_cvt_pk_bf16_f32 %0, %1, %2" : "=v"(r) : "v"(lo), "v"(hi)); return r; }
; template <int DK>
; DI void attn_pass(const AttnSrc& s, const int q0, const float sc, LAS unsigned char* lds, f32x16 (&O)[4]) {
;     ...
; #pragma unroll
;         for (int j = 0; j < 16; ++j) { p0[j] = __builtin_amdgcn_exp2f(p0[j]); p1[j] = __builtin_amdgcn_exp2f(p1[j]); rs += p0[j] + p1[j]; }
;       } else {
;         const float cand = mx * sc;
;         const bool grow = cand > mrun + 8.f;
;         if (__builtin_amdgcn_ballot_w64(grow) != 0ull) {
;           const float mnew = grow ? cand : mrun;
;           const float alpha = __builtin_amdgcn_exp2f(mrun - mnew);
;           mrun = mnew; lrun *= alpha;
; #pragma unroll
;           for (int i = 0; i < 4; ++i)
; #pragma unroll
;             for (int j = 0; j < 16; ++j) O[i][j] *= alpha;
;         }
; #pragma unroll
;         for (int j = 0; j < 16; ++j) { p0[j] = __builtin_amdgcn_exp2f(p0[j] * sc - mrun); p1[j] = __builtin_amdgcn_exp2f(p1[j] * sc - mrun); rs += p0[j] + p1[j]; }
;       }
;       lrun += rs;
;       bf16x8 pb[4];
;       { u32x4 w;
;         w.x = cvt_pk_bf16(p0[0], p0[1]); w.y = cvt_pk_bf16(p0[2], p0[3]); w.z = cvt_pk_bf16(p0[4], p0[5]); w.w = cvt_pk_bf16(p0[6], p0[7]); pb[0] = __builtin_bit_cast(bf16x8, w);
;         w.x = cvt_pk_bf16(p0[8], p0[9]); w.y = cvt_pk_bf16(p0[10], p0[11]); w.z = cvt_pk_bf16(p0[12], p0[13]); w.w = cvt_pk_bf16(p0[14], p0[15]); pb[1] = __builtin_bit_cast(bf16x8, w);
;         w.x = cvt_pk_bf16(p1[0], p1[1]); w.y = cvt_pk_bf16(p1[2], p1[3]); w.z = cvt_pk_bf16(p1[4], p1[5]); w.w = cvt_pk_bf16(p1[6], p1[7]); pb[2] = __builtin_bit_cast(bf16x8, w);
;         w.x = cvt_pk_bf16(p1[8], p1[9]); w.y = cvt_pk_bf16(p1[10], p1[11]); w.z = cvt_pk_bf16(p1[12], p1[13]); w.w = cvt_pk_bf16(p1[14], p1[15]); pb[3] = __builtin_bit_cast(bf16x8, w); }
; #pragma unroll
;       for (int vt = 0; vt < 4; ++vt) {
;         if (vt + 1 < 4) vload(vt + 1, (vt + 1) & 1);
;         __builtin_amdgcn_s_setprio(1);
; #pragma unroll
;         for (int ks = 0; ks < 4; ++ks) O[vt] = __builtin_amdgcn_mfma_f32_32x32x16_bf16(vf[vt & 1][ks], pb[ks], O[vt], 0, 0, 0);
;         __builtin_amdgcn_s_setprio(0);
;       }
.Ln64_exp:
	v_exp_f32_e32 v112, v112
	v_exp_f32_e32 v113, v113
	v_exp_f32_e32 v114, v114
	v_exp_f32_e32 v115, v115
	v_exp_f32_e32 v116, v116
	v_exp_f32_e32 v117, v117
	v_exp_f32_e32 v118, v118
	v_exp_f32_e32 v119, v119
	v_add_f32_e32 v0, v112, v113
	v_add_f32_e32 v15, v114, v115
	v_add_f32_e32 v0, v0, v116
	v_add_f32_e32 v15, v15, v117
	v_add_f32_e32 v0, v0, v118
	v_add_f32_e32 v15, v15, v119
	v_cvt_pk_bf16_f32 v112, v112, v113
	v_cvt_pk_bf16_f32 v113, v114, v115
	v_cvt_pk_bf16_f32 v114, v116, v117
	v_cvt_pk_bf16_f32 v115, v118, v119
	ds_read_b64_tr_b16 v[230:231], v246 offset:12288
	ds_read_b64_tr_b16 v[232:233], v246 offset:14336
	ds_read_b64_tr_b16 v[234:235], v247 offset:12288
	ds_read_b64_tr_b16 v[236:237], v247 offset:14336
	ds_read_b64_tr_b16 v[238:239], v248 offset:12288
	ds_read_b64_tr_b16 v[240:241], v248 offset:14336
	ds_read_b64_tr_b16 v[242:243], v249 offset:12288
	ds_read_b64_tr_b16 v[244:245], v249 offset:14336
	s_setprio 1
	s_waitcnt lgkmcnt(14)
	v_mfma_f32_32x32x16_bf16 v[64:79], v[2:5], v[112:115], v[64:79]
	s_waitcnt lgkmcnt(12)
	v_mfma_f32_32x32x16_bf16 v[48:63], v[6:9], v[112:115], v[48:63]
	s_waitcnt lgkmcnt(10)
	v_mfma_f32_32x32x16_bf16 v[32:47], v[10:13], v[112:115], v[32:47]
	s_waitcnt lgkmcnt(8)
	v_mfma_f32_32x32x16_bf16 v[16:31], v[144:147], v[112:115], v[16:31]
	v_exp_f32_e32 v120, v120
	v_exp_f32_e32 v121, v121
	v_exp_f32_e32 v122, v122
	v_exp_f32_e32 v123, v123
	v_exp_f32_e32 v124, v124
	v_exp_f32_e32 v125, v125
	v_exp_f32_e32 v126, v126
	v_exp_f32_e32 v127, v127
	v_add_f32_e32 v0, v0, v120
	v_add_f32_e32 v15, v15, v121
	v_add_f32_e32 v0, v0, v122
	v_add_f32_e32 v15, v15, v123
	v_add_f32_e32 v0, v0, v124
	v_add_f32_e32 v15, v15, v125
	v_add_f32_e32 v0, v0, v126
	v_add_f32_e32 v15, v15, v127
	v_cvt_pk_bf16_f32 v116, v120, v121
	v_cvt_pk_bf16_f32 v117, v122, v123
	v_cvt_pk_bf16_f32 v118, v124, v125
	v_cvt_pk_bf16_f32 v119, v126, v127
	ds_read_b64_tr_b16 v[2:3], v246 offset:16384
	ds_read_b64_tr_b16 v[4:5], v246 offset:18432
	ds_read_b64_tr_b16 v[6:7], v247 offset:16384
	ds_read_b64_tr_b16 v[8:9], v247 offset:18432
	ds_read_b64_tr_b16 v[10:11], v248 offset:16384
	ds_read_b64_tr_b16 v[12:13], v248 offset:18432
	ds_read_b64_tr_b16 v[144:145], v249 offset:16384
	ds_read_b64_tr_b16 v[146:147], v249 offset:18432
	s_waitcnt lgkmcnt(14)
	v_mfma_f32_32x32x16_bf16 v[64:79], v[230:233], v[116:119], v[64:79]
	s_waitcnt lgkmcnt(12)
	v_mfma_f32_32x32x16_bf16 v[48:63], v[234:237], v[116:119], v[48:63]
	s_waitcnt lgkmcnt(10)
	v_mfma_f32_32x32x16_bf16 v[32:47], v[238:241], v[116:119], v[32:47]
	s_waitcnt lgkmcnt(8)
	v_mfma_f32_32x32x16_bf16 v[16:31], v[242:245], v[116:119], v[16:31]
	v_exp_f32_e32 v96, v96
	v_exp_f32_e32 v97, v97
	v_exp_f32_e32 v98, v98
	v_exp_f32_e32 v99, v99
	v_exp_f32_e32 v100, v100
	v_exp_f32_e32 v101, v101
	v_exp_f32_e32 v102, v102
	v_exp_f32_e32 v103, v103
	v_add_f32_e32 v0, v0, v96
	v_add_f32_e32 v15, v15, v97
	v_add_f32_e32 v0, v0, v98
	v_add_f32_e32 v15, v15, v99
	v_add_f32_e32 v0, v0, v100
	v_add_f32_e32 v15, v15, v101
	v_add_f32_e32 v0, v0, v102
	v_add_f32_e32 v15, v15, v103
	v_cvt_pk_bf16_f32 v96, v96, v97
	v_cvt_pk_bf16_f32 v97, v98, v99
	v_cvt_pk_bf16_f32 v98, v100, v101
	v_cvt_pk_bf16_f32 v99, v102, v103
	ds_read_b64_tr_b16 v[230:231], v246 offset:20480
	ds_read_b64_tr_b16 v[232:233], v246 offset:22528
	ds_read_b64_tr_b16 v[234:235], v247 offset:20480
	ds_read_b64_tr_b16 v[236:237], v247 offset:22528
	ds_read_b64_tr_b16 v[238:239], v248 offset:20480
	ds_read_b64_tr_b16 v[240:241], v248 offset:22528
	ds_read_b64_tr_b16 v[242:243], v249 offset:20480
	ds_read_b64_tr_b16 v[244:245], v249 offset:22528
	s_waitcnt lgkmcnt(14)
	v_mfma_f32_32x32x16_bf16 v[64:79], v[2:5], v[96:99], v[64:79]
	s_waitcnt lgkmcnt(12)
	v_mfma_f32_32x32x16_bf16 v[48:63], v[6:9], v[96:99], v[48:63]
	s_waitcnt lgkmcnt(10)
	v_mfma_f32_32x32x16_bf16 v[32:47], v[10:13], v[96:99], v[32:47]
	s_waitcnt lgkmcnt(8)
	v_mfma_f32_32x32x16_bf16 v[16:31], v[144:147], v[96:99], v[16:31]
	v_exp_f32_e32 v104, v104
	v_exp_f32_e32 v105, v105
	v_exp_f32_e32 v106, v106
	v_exp_f32_e32 v107, v107
	v_exp_f32_e32 v108, v108
	v_exp_f32_e32 v109, v109
	v_exp_f32_e32 v110, v110
	v_exp_f32_e32 v111, v111
	v_add_f32_e32 v0, v0, v104
	v_add_f32_e32 v15, v15, v105
	v_add_f32_e32 v0, v0, v106
	v_add_f32_e32 v15, v15, v107
	v_add_f32_e32 v0, v0, v108
	v_add_f32_e32 v15, v15, v109
	v_add_f32_e32 v0, v0, v110
	v_add_f32_e32 v15, v15, v111
	v_cvt_pk_bf16_f32 v100, v104, v105
	v_cvt_pk_bf16_f32 v101, v106, v107
	v_cvt_pk_bf16_f32 v102, v108, v109
	v_cvt_pk_bf16_f32 v103, v110, v111
	s_nop 1
	s_waitcnt lgkmcnt(6)
	v_mfma_f32_32x32x16_bf16 v[64:79], v[230:233], v[100:103], v[64:79]
	s_waitcnt lgkmcnt(4)
	v_mfma_f32_32x32x16_bf16 v[48:63], v[234:237], v[100:103], v[48:63]
	s_waitcnt lgkmcnt(2)
	v_mfma_f32_32x32x16_bf16 v[32:47], v[238:241], v[100:103], v[32:47]
	s_waitcnt lgkmcnt(0)
	v_mfma_f32_32x32x16_bf16 v[16:31], v[242:245], v[100:103], v[16:31]
	s_setprio 0
	v_add_f32_e32 v0, v0, v15
	v_add_f32_e32 v14, v14, v0
	s_branch .LBB0_101
.Ln64_skip:
	s_cmp_ge_u32 s54, s41
	s_cbranch_scc1 .LBB0_101
	s_mul_i32 s18, s58, 0x6000
	v_lshl_add_u64 v[2:3], v[170:171], 0, s[14:15]
	s_add_i32 s19, s18, s46
	s_mov_b32 s62, m0
	s_mov_b32 m0, s19
	s_nop 0
	global_load_lds_dwordx4 v[2:3], off
	s_mov_b32 m0, s62
	v_lshl_add_u64 v[2:3], v[168:169], 0, s[14:15]
	s_add_i32 s19, s18, s47
	s_mov_b32 s62, m0
	s_mov_b32 m0, s19
	s_nop 0
	global_load_lds_dwordx4 v[2:3], off
	s_mov_b32 m0, s62
	v_lshl_add_u64 v[2:3], v[166:167], 0, s[14:15]
	s_add_i32 s18, s18, s52
	s_mov_b32 s19, m0
	s_mov_b32 m0, s18
	s_nop 0
	global_load_lds_dwordx4 v[2:3], off
	s_mov_b32 m0, s19
	s_branch .LBB0_101

; template <int DK>
; DI void attn_pass(const AttnSrc& s, const int q0, const float sc, LAS unsigned char* lds, f32x16 (&O)[4]) {
;     ...
;   const bf16_t* kp[KP]; int kstr[KP]; const bf16_t* vp[2];
; #pragma unroll
;   for (int i = 0; i < KP; ++i) {
;     const int o = (wid + 8 * i) * 1024 + lane * 16, row = o / ROWB, pc = (o % ROWB) >> 4;
;     const int lc = (DK == 64) ? (pc ^ (row & 7)) : ((pc & ~7) | ((pc & 7) ^ ((row >> 1) & 7)));
;     const int e = lc * 8;
;     if (e < s.nk0) { kp[i] = s.k0 + (size_t)row * s.ldk0 + e; kstr[i] = 64 * s.ldk0; } else { kp[i] = s.k1 + (size_t)row * s.ldk1 + (e - s.nk0); kstr[i] = 64 * s.ldk1; }
;   }
; #pragma unroll
;   for (int i = 0; i < 2; ++i) {
;     const int o = (wid + 8 * i) * 1024 + lane * 16, row = o >> 8, pc = (o >> 4) & 15;
;     const int lc = (((pc >> 2) ^ (row & 3)) << 2) | (pc & 3);
;     vp[i] = s.v + (size_t)row * s.ldv + lc * 8;
;   }
;   const int vstr = 64 * s.ldv;
;   const unsigned lds0 = (unsigned)reinterpret_cast<__UINTPTR_TYPE__>(lds);
;   auto issue = [&](int t, int buf) {
; #pragma unroll
;     for (int i = 0; i < KP; ++i) glds16(kp[i] + (size_t)t * kstr[i], (unsigned)__builtin_amdgcn_readfirstlane(lds0 + buf * STG + (wid + 8 * i) * 1024));
; #pragma unroll
;     for (int i = 0; i < 2; ++i) glds16(vp[i] + (size_t)t * vstr, (unsigned)__builtin_amdgcn_readfirstlane(lds0 + buf * STG + KSZ + (wid + 8 * i) * 1024));
;   };
; #pragma unroll
;   for (int i = 0; i < DPF; ++i) issue(i, i);
.LBB0_123:
	v_mov_b32_e32 v16, v163
	s_waitcnt vmcnt(0)
	s_nop 0
	v_readfirstlane_b32 s12, v16
	s_ashr_i32 s40, s12, 6
	v_and_b32_e32 v18, 63, v16
	s_lshl_b32 s41, s40, 10
	v_lshl_or_b32 v17, v18, 4, s41
	v_mul_hi_i32 v0, v17, s60
	v_lshrrev_b32_e32 v2, 31, v0
	v_ashrrev_i32_e32 v0, 6, v0
	v_add_u32_e32 v8, v0, v2
	v_mul_i32_i24_e32 v0, 0x180, v8
	v_sub_u32_e32 v0, v17, v0
	v_ashrrev_i32_e32 v0, 4, v0
	v_lshrrev_b32_e32 v2, 1, v8
	v_bitop3_b32 v0, v2, v0, 7 bitop3:0x6c
	v_lshlrev_b32_e32 v6, 3, v0
	v_cmp_lt_i32_e32 vcc, 15, v0
	v_ashrrev_i32_e32 v9, 31, v8
	s_and_saveexec_b64 s[12:13], vcc
	s_xor_b64 s[12:13], exec, s[12:13]
	v_mul_hi_i32_i24_e32 v3, 0xc00, v8
	v_mul_i32_i24_e32 v2, 0xc00, v8
	v_lshl_add_u64 v[2:3], s[8:9], 0, v[2:3]
	v_mov_b32_e32 v7, v1
	v_lshl_add_u64 v[2:3], v[6:7], 1, v[2:3]
	v_lshl_add_u64 v[2:3], v[2:3], 0, s[34:35]
	s_or_saveexec_b64 s[12:13], s[12:13]
	v_mov_b64_e32 v[4:5], 0x18000
	s_xor_b64 exec, exec, s[12:13]
	v_lshlrev_b64 v[2:3], 12, v[8:9]
	v_lshl_add_u64 v[2:3], s[6:7], 0, v[2:3]
	v_ashrrev_i32_e32 v7, 31, v6
	v_lshl_add_u64 v[2:3], v[6:7], 1, v[2:3]
	v_mov_b64_e32 v[4:5], 0x20000
	s_or_b64 exec, exec, s[12:13]
	v_add_u32_e32 v5, 0x2000, v17
	v_mul_hi_i32 v0, v5, s60
	v_lshrrev_b32_e32 v6, 31, v0
	v_ashrrev_i32_e32 v0, 6, v0
	v_add_u32_e32 v10, v0, v6
	v_mul_i32_i24_e32 v0, 0x180, v10
	v_sub_u32_e32 v0, v5, v0
	v_ashrrev_i32_e32 v0, 4, v0
	v_lshrrev_b32_e32 v6, 1, v10
	v_bitop3_b32 v6, v6, v0, 7 bitop3:0x6c
	v_lshlrev_b32_e32 v0, 3, v6
	v_cmp_lt_i32_e32 vcc, 15, v6
	v_ashrrev_i32_e32 v11, 31, v10
	s_and_saveexec_b64 s[12:13], vcc
	s_xor_b64 s[12:13], exec, s[12:13]
	v_mul_hi_i32_i24_e32 v7, 0xc00, v10
	v_mul_i32_i24_e32 v6, 0xc00, v10
	v_lshl_add_u64 v[6:7], s[8:9], 0, v[6:7]
	v_lshl_add_u64 v[6:7], v[0:1], 1, v[6:7]
	v_lshl_add_u64 v[6:7], v[6:7], 0, s[34:35]
	s_or_saveexec_b64 s[12:13], s[12:13]
	v_mov_b64_e32 v[8:9], 0x18000
	s_xor_b64 exec, exec, s[12:13]
	v_lshlrev_b64 v[6:7], 12, v[10:11]
	v_lshl_add_u64 v[6:7], s[6:7], 0, v[6:7]
	v_ashrrev_i32_e32 v9, 31, v0
	v_mov_b32_e32 v8, v0
	v_lshl_add_u64 v[6:7], v[8:9], 1, v[6:7]
	v_mov_b64_e32 v[8:9], 0x20000
	s_or_b64 exec, exec, s[12:13]
	v_add_u32_e32 v0, 0x4000, v17
	v_mul_hi_i32 v9, v0, s60
	v_lshrrev_b32_e32 v10, 31, v9
	v_ashrrev_i32_e32 v9, 6, v9
	v_add_u32_e32 v14, v9, v10
	v_mul_i32_i24_e32 v9, 0x180, v14
	v_sub_u32_e32 v0, v0, v9
	v_ashrrev_i32_e32 v0, 4, v0
	v_lshrrev_b32_e32 v9, 1, v14
	v_bitop3_b32 v9, v9, v0, 7 bitop3:0x6c
	v_lshlrev_b32_e32 v0, 3, v9
	v_cmp_lt_i32_e32 vcc, 15, v9
	v_ashrrev_i32_e32 v15, 31, v14
	s_and_saveexec_b64 s[12:13], vcc
	s_xor_b64 s[12:13], exec, s[12:13]
	v_mul_hi_i32_i24_e32 v11, 0xc00, v14
	v_mul_i32_i24_e32 v10, 0xc00, v14
	v_lshl_add_u64 v[10:11], s[8:9], 0, v[10:11]
	v_lshl_add_u64 v[10:11], v[0:1], 1, v[10:11]
	v_lshl_add_u64 v[10:11], v[10:11], 0, s[34:35]
	s_or_saveexec_b64 s[12:13], s[12:13]
	v_mov_b64_e32 v[12:13], 0x18000
	s_xor_b64 exec, exec, s[12:13]
	v_lshlrev_b64 v[10:11], 12, v[14:15]
	v_lshl_add_u64 v[10:11], s[6:7], 0, v[10:11]
	v_ashrrev_i32_e32 v13, 31, v0
	v_mov_b32_e32 v12, v0
	v_lshl_add_u64 v[10:11], v[12:13], 1, v[10:11]
	v_mov_b64_e32 v[12:13], 0x20000
	s_or_b64 exec, exec, s[12:13]
	v_ashrrev_i32_e32 v14, 8, v17
	v_lshlrev_b32_e32 v0, 2, v14
	v_and_b32_e32 v21, 3, v16
	v_xor_b32_e32 v0, v0, v16
	v_ashrrev_i32_e32 v15, 31, v14
	v_and_or_b32 v0, v0, 12, v21
	v_lshlrev_b64 v[14:15], 12, v[14:15]
	v_lshl_add_u64 v[14:15], s[6:7], 0, v[14:15]
	v_lshlrev_b32_e32 v0, 4, v0
	v_ashrrev_i32_e32 v20, 8, v5
	s_xor_b64 s[12:13], s[14:15], -1
	v_lshl_add_u64 v[14:15], v[14:15], 0, v[0:1]
	v_lshlrev_b32_e32 v0, 2, v20
	s_and_b64 s[14:15], s[14:15], exec
	v_xor_b32_e32 v0, v0, v16
	s_cselect_b32 s33, s22, s23
	v_and_or_b32 v0, v0, 12, v21
	v_ashrrev_i32_e32 v21, 31, v20
	s_add_i32 s41, s41, 0
	s_mov_b32 s14, m0
	s_mov_b32 m0, s41
	s_nop 0
	global_load_lds_dwordx4 v[2:3], off
	s_mov_b32 m0, s14
	v_lshlrev_b64 v[20:21], 12, v[20:21]
	s_add_i32 s42, s41, 0x2000
	s_mov_b32 s14, m0
	s_mov_b32 m0, s42
	s_nop 0
	global_load_lds_dwordx4 v[6:7], off
	s_mov_b32 m0, s14
	v_lshl_add_u64 v[20:21], s[6:7], 0, v[20:21]
	v_lshlrev_b32_e32 v0, 4, v0
	s_add_i32 s43, s41, 0x4000
	s_mov_b32 s14, m0
	s_mov_b32 m0, s43
	s_nop 0
	global_load_lds_dwordx4 v[10:11], off
	s_mov_b32 m0, s14
	v_lshrrev_b32_e32 v13, 5, v18
	v_lshl_add_u64 v[18:19], v[14:15], 0, s[36:37]
	v_lshl_add_u64 v[20:21], v[20:21], 0, v[0:1]
	s_add_i32 s44, s41, 0x6000
	s_mov_b32 s14, m0
	s_mov_b32 m0, s44
	s_nop 0
	global_load_lds_dwordx4 v[18:19], off
	s_mov_b32 m0, s14
	v_lshlrev_b32_e32 v170, 1, v4
	v_mov_b32_e32 v171, v1
	v_lshl_add_u64 v[22:23], v[20:21], 0, s[36:37]
	s_add_i32 s45, s41, 0x8000
	s_mov_b32 s14, m0
	s_mov_b32 m0, s45
	s_nop 0
	global_load_lds_dwordx4 v[22:23], off
	s_mov_b32 m0, s14
	v_lshl_add_u64 v[18:19], v[2:3], 0, v[170:171]
	v_lshlrev_b32_e32 v172, 1, v8
	v_mov_b32_e32 v173, v1
	s_add_i32 s14, s41, 0xa000
	s_mov_b32 s15, m0
	s_mov_b32 m0, s14
	s_nop 0
	global_load_lds_dwordx4 v[18:19], off
	s_mov_b32 m0, s15
	v_lshl_add_u64 v[18:19], v[6:7], 0, v[172:173]
	v_lshlrev_b32_e32 v174, 1, v12
; DI unsigned cvt_pk_bf16(float lo, float hi) { unsigned r; asm volatile("v_cvt_pk_bf16_f32 %0, %1, %2" : "=v"(r) : "v"(lo), "v"(hi)); return r; }
; DI float bf_lo(unsigned w) { return __uint_as_float(w << 16); }
; DI float bf_hi(unsigned w) { return __uint_as_float(w & 0xffff0000u); }
; template <int DK>
; DI void attn_pass(const AttnSrc& s, const int q0, const float sc, LAS unsigned char* lds, f32x16 (&O)[4]) {
;     ...
;   bf16x8 qf[NS];
; #pragma unroll
;   for (int i = 0; i < NS; ++i) qf[i] = *(const bf16x8*)(s.q + (size_t)(qw0 + r) * s.ldq + 16 * i + 8 * h);
; #pragma unroll
;   for (int i = 0; i < NS; ++i) asm volatile("" : "+v"(qf[i]));
;   constexpr bool REL = (DK == 64);
;   if (REL) {
; #pragma unroll
;   for (int i = 0; i < NS; ++i) {
;     const u32x4 w = __builtin_bit_cast(u32x4, qf[i]); u32x4 o;
;     o.x = cvt_pk_bf16(bf_lo(w.x) * sc, bf_hi(w.x) * sc); o.y = cvt_pk_bf16(bf_lo(w.y) * sc, bf_hi(w.y) * sc);
;     o.z = cvt_pk_bf16(bf_lo(w.z) * sc, bf_hi(w.z) * sc); o.w = cvt_pk_bf16(bf_lo(w.w) * sc, bf_hi(w.w) * sc);
;     qf[i] = __builtin_bit_cast(bf16x8, o);
;   }
;   }
;   f32x16 negm;
; #pragma unroll
;   for (int j = 0; j < 16; ++j) negm[j] = 0.f;
;   if (REL) asm volatile("" : "+v"(negm));
;   const int kx = (DK == 64) ? (r & 7) : ((r >> 1) & 7);
;   const int krow = r * ROWB;
;   const int i15 = lane & 15;
;   const int vrow = (4 * h + (i15 >> 2)) * 256 + ((lane >> 4) & 1) * 32 + (lane & 3) * 8;
;   const int vx = (i15 >> 2) & 3;
;   int buf = 0, pbuf = DPF;
;     ...
;     buf = (buf + 1 == NBUF) ? 0 : buf + 1; pbuf = (pbuf + 1 == NBUF) ? 0 : pbuf + 1;
	v_mov_b32_e32 v175, v1
	s_add_i32 s14, s41, 0xc000
	s_mov_b32 s15, m0
	s_mov_b32 m0, s14
	s_nop 0
	global_load_lds_dwordx4 v[18:19], off
	s_mov_b32 m0, s15
	v_lshl_add_u64 v[18:19], v[10:11], 0, v[174:175]
	s_lshl_b32 s40, s40, 5
	s_add_i32 s14, s41, 0xe000
	s_mov_b32 s15, m0
	s_mov_b32 m0, s14
	s_nop 0
	global_load_lds_dwordx4 v[18:19], off
	s_mov_b32 m0, s15
	v_lshl_add_u64 v[18:19], v[14:15], 0, s[90:91]
	v_and_b32_e32 v9, 31, v16
	s_add_i32 s40, s40, s33
	s_add_i32 s14, s41, 0x10000
	s_mov_b32 s15, m0
	s_mov_b32 m0, s14
	s_nop 0
	global_load_lds_dwordx4 v[18:19], off
	s_mov_b32 m0, s15
	v_lshl_add_u64 v[18:19], v[20:21], 0, s[90:91]
	s_add_i32 s14, s41, 0x12000
	s_mov_b32 s15, m0
	s_mov_b32 m0, s14
	s_nop 0
	global_load_lds_dwordx4 v[18:19], off
	s_mov_b32 m0, s15
	v_or_b32_e32 v167, s40, v9
	v_mov_b64_e32 v[18:19], s[4:5]
	v_mad_i64_i32 v[18:19], s[14:15], v167, s88, v[18:19]
	v_lshlrev_b32_e32 v0, 4, v13
	v_lshl_add_u64 v[18:19], v[18:19], 0, v[0:1]
	global_load_dwordx4 v[98:101], v[18:19], off
	global_load_dwordx4 v[102:105], v[18:19], off offset:32
	global_load_dwordx4 v[106:109], v[18:19], off offset:64
	global_load_dwordx4 v[110:113], v[18:19], off offset:96
	global_load_dwordx4 v[114:117], v[18:19], off offset:128
	global_load_dwordx4 v[118:121], v[18:19], off offset:160
	global_load_dwordx4 v[122:125], v[18:19], off offset:192
	global_load_dwordx4 v[126:129], v[18:19], off offset:224
	global_load_dwordx4 v[130:133], v[18:19], off offset:256
	global_load_dwordx4 v[134:137], v[18:19], off offset:288
	global_load_dwordx4 v[138:141], v[18:19], off offset:320
	global_load_dwordx4 v[142:145], v[18:19], off offset:352
	v_lshrrev_b32_e32 v0, 1, v16
	v_bfe_u32 v5, v16, 1, 3
	v_bitop3_b32 v0, v13, v0, 7 bitop3:0x78
	v_lshlrev_b32_e32 v209, 4, v0
	v_bitop3_b32 v0, v13, v5, 2 bitop3:0x36
	v_lshlrev_b32_e32 v210, 4, v0
	v_bitop3_b32 v0, v13, v5, 4 bitop3:0x36
	v_lshlrev_b32_e32 v213, 4, v0
	v_bitop3_b32 v0, v13, v5, 6 bitop3:0x36
	v_lshlrev_b32_e32 v214, 4, v0
	v_lshlrev_b32_e32 v0, 2, v12
	v_lshl_add_u64 v[180:181], v[10:11], 0, v[0:1]
	v_lshlrev_b32_e32 v0, 2, v8
	v_mul_u32_u24_e32 v204, 0x180, v9
	v_bfe_u32 v9, v16, 2, 2
	v_lshl_add_u64 v[178:179], v[14:15], 0, s[92:93]
	v_lshl_add_u64 v[182:183], v[6:7], 0, v[0:1]
	v_lshlrev_b32_e32 v0, 2, v4
	v_mov_b32_e32 v14, v1
	v_mov_b32_e32 v15, v1
	s_add_i32 s14, s33, 0x100
	v_lshlrev_b32_e32 v205, 10, v13
	v_lshlrev_b32_e32 v206, 8, v9
	v_lshlrev_b32_e32 v17, 1, v16
	v_lshlrev_b32_e32 v16, 3, v16
	v_lshlrev_b32_e32 v211, 6, v9
	v_lshlrev_b32_e32 v212, 2, v13
	v_lshl_add_u64 v[176:177], v[20:21], 0, s[92:93]
	v_lshl_add_u64 v[184:185], v[2:3], 0, v[0:1]
	v_mov_b32_e32 v0, v1
	v_mov_b32_e32 v2, v1
	v_mov_b32_e32 v3, v1
	v_mov_b32_e32 v4, v1
	v_mov_b32_e32 v5, v1
	v_mov_b32_e32 v6, v1
	v_mov_b32_e32 v7, v1
	v_mov_b32_e32 v8, v1
	v_mov_b32_e32 v9, v1
	v_mov_b32_e32 v10, v1
	v_mov_b32_e32 v11, v1
	v_mov_b32_e32 v12, v1
	v_mov_b32_e32 v13, v1
	v_mov_b64_e32 v[64:65], v[14:15]
	v_mov_b64_e32 v[48:49], v[14:15]
	v_mov_b64_e32 v[32:33], v[14:15]
	s_lshr_b32 s47, s14, 6
	v_and_b32_e32 v207, 32, v17
	v_and_b32_e32 v208, 24, v16
	v_mov_b64_e32 v[62:63], v[12:13]
	v_mov_b64_e32 v[60:61], v[10:11]
	v_mov_b64_e32 v[58:59], v[8:9]
	v_mov_b64_e32 v[56:57], v[6:7]
	v_mov_b64_e32 v[54:55], v[4:5]
	v_mov_b64_e32 v[52:53], v[2:3]
	v_mov_b64_e32 v[50:51], v[0:1]
	v_mov_b64_e32 v[46:47], v[12:13]
	v_mov_b64_e32 v[44:45], v[10:11]
	v_mov_b64_e32 v[42:43], v[8:9]
	v_mov_b64_e32 v[40:41], v[6:7]
	v_mov_b64_e32 v[38:39], v[4:5]
	v_mov_b64_e32 v[36:37], v[2:3]
	v_mov_b64_e32 v[34:35], v[0:1]
	v_mov_b64_e32 v[30:31], v[12:13]
	v_mov_b64_e32 v[28:29], v[10:11]
	v_mov_b64_e32 v[26:27], v[8:9]
	v_mov_b64_e32 v[24:25], v[6:7]
	v_mov_b64_e32 v[22:23], v[4:5]
	v_mov_b64_e32 v[20:21], v[2:3]
	v_mov_b64_e32 v[18:19], v[0:1]
	v_mov_b64_e32 v[16:17], v[14:15]
	s_mov_b32 s46, 2
	s_add_i32 s52, s47, -1
	s_or_b32 s53, s40, 31
	v_xor_b32_e32 v215, 64, v211
	v_xor_b32_e32 v216, 0x80, v211
	v_xor_b32_e32 v217, 0xc0, v211
	s_mov_b32 s54, 0
	v_mov_b32_e32 v218, 0
	v_mov_b32_e32 v219, 0xff800000
	s_mov_b32 s55, 63
	v_mov_b64_e32 v[14:15], v[12:13]
	v_mov_b64_e32 v[12:13], v[10:11]
	v_mov_b64_e32 v[10:11], v[8:9]
	v_mov_b64_e32 v[8:9], v[6:7]
	v_mov_b64_e32 v[6:7], v[4:5]
	v_mov_b64_e32 v[4:5], v[2:3]
	v_mov_b64_e32 v[2:3], v[0:1]
	s_mov_b32 s56, 0
	s_waitcnt vmcnt(11)
	s_waitcnt vmcnt(10)
	s_waitcnt vmcnt(9)
	s_waitcnt vmcnt(8)
	s_waitcnt vmcnt(7)
	s_waitcnt vmcnt(6)
	s_waitcnt vmcnt(5)
	s_waitcnt vmcnt(4)
	s_waitcnt vmcnt(3)
	s_waitcnt vmcnt(2)
	s_waitcnt vmcnt(1)
	s_waitcnt vmcnt(0)
	s_branch .LBB0_138
.LBB0_137:
	s_add_i32 s15, s54, 1
	s_cmp_lg_u32 s15, 3
	s_cselect_b32 s54, s15, 0
	s_add_i32 s15, s46, 1
	s_cmp_lg_u32 s15, 3
	s_cselect_b32 s46, s15, 0
	s_add_i32 s55, s55, 64
	s_add_i32 s56, s14, -1
	v_lshl_add_u64 v[176:177], v[176:177], 0, s[24:25]
	v_lshl_add_u64 v[178:179], v[178:179], 0, s[24:25]
	v_lshl_add_u64 v[180:181], v[180:181], 0, v[174:175]
	v_lshl_add_u64 v[182:183], v[182:183], 0, v[172:173]
	s_cmp_lg_u32 s56, s47
	v_lshl_add_u64 v[184:185], v[184:185], 0, v[170:171]
	s_cbranch_scc0 .LBB0_122

; #define LAS __attribute__((address_space(3)))
; template <int DK>
; DI void attn_pass(const AttnSrc& s, const int q0, const float sc, LAS unsigned char* lds, f32x16 (&O)[4]) {
;     ...
;     __builtin_amdgcn_s_barrier();
;     asm volatile("" ::: "memory");
;     if (t + DPF < NT) issue(t + DPF, pbuf);
;     if (64 * t <= qw0 + 31) {
;       LAS unsigned char* Kb = lds + buf * STG; LAS unsigned char* Vb = lds + buf * STG + KSZ;
;       f32x16 p0, p1;
;       constexpr int GS = (DK == 64) ? 4 : 2, NG = NS / GS;
;       bf16x8 kfa[2][GS], kfb[2][GS];
;       auto kload = [&](int g, int slot) {
; #pragma unroll
;         for (int j = 0; j < GS; ++j) { const int lc = 2 * (g * GS + j) + h; const int ph = (DK == 64) ? (lc ^ kx) : ((lc & ~7) | ((lc & 7) ^ kx));
;           kfa[slot][j] = *(const LAS bf16x8*)(Kb + krow + ph * 16); kfb[slot][j] = *(const LAS bf16x8*)(Kb + krow + 32 * ROWB + ph * 16); }
;       };
;       kload(0, 0);
; #pragma unroll
;       for (int g = 0; g < NG; ++g) {
;         if (g + 1 < NG) kload(g + 1, (g + 1) & 1);
;         __builtin_amdgcn_s_setprio(1);
; #pragma unroll
;         for (int j = 0; j < GS; ++j) {
;           if (g == 0 && j == 0) {
;             if (REL) {
;               p0 = __builtin_amdgcn_mfma_f32_32x32x16_bf16(kfa[0][0], qf[0], negm, 0, 0, 0);
;               p1 = __builtin_amdgcn_mfma_f32_32x32x16_bf16(kfb[0][0], qf[0], negm, 0, 0, 0);
;             } else {
;               f32x16 z;
; #pragma unroll
;               for (int jj = 0; jj < 16; ++jj) z[jj] = 0.f;
;               p0 = __builtin_amdgcn_mfma_f32_32x32x16_bf16(kfa[0][0], qf[0], z, 0, 0, 0);
;               p1 = __builtin_amdgcn_mfma_f32_32x32x16_bf16(kfb[0][0], qf[0], z, 0, 0, 0);
;             }
;           } else {
;             p0 = __builtin_amdgcn_mfma_f32_32x32x16_bf16(kfa[g & 1][j], qf[g * GS + j], p0, 0, 0, 0);
;             p1 = __builtin_amdgcn_mfma_f32_32x32x16_bf16(kfb[g & 1][j], qf[g * GS + j], p1, 0, 0, 0);
;           }
;         }
;         __builtin_amdgcn_s_setprio(0);
;       }
;       bf16x8 vf[2][4];
;       auto vload = [&](int vt, int slot) {
;         const int vcol = vrow + ((vt ^ vx) << 6);
; #pragma unroll
;         for (int ks = 0; ks < 4; ++ks) {
;           const s16x4 lo = __builtin_bit_cast(s16x4, __builtin_amdgcn_ds_read_tr16_b64_v4i16((LAS s16x4*)(Vb + vcol + ks * 16 * 256)));
.LBB0_142:
	s_barrier
	s_add_i32 s14, s56, 2
	s_sub_i32 s15, s55, 63
	s_cmp_gt_i32 s15, s53
	s_cbranch_scc0 .Ln192_act
	s_cmp_ge_u32 s14, s47
	s_cbranch_scc1 .LBB0_137
	s_mul_i32 s15, s46, 0xa000
	s_add_i32 s56, s15, s41
	s_mov_b32 s57, m0
	s_mov_b32 m0, s56
	s_nop 0
	global_load_lds_dwordx4 v[184:185], off
	s_mov_b32 m0, s57
	s_add_i32 s56, s15, s42
	s_mov_b32 s57, m0
	s_mov_b32 m0, s56
	s_nop 0
	global_load_lds_dwordx4 v[182:183], off
	s_mov_b32 m0, s57
	s_add_i32 s56, s15, s43
	s_mov_b32 s57, m0
	s_mov_b32 m0, s56
	s_nop 0
	global_load_lds_dwordx4 v[180:181], off
	s_mov_b32 m0, s57
	s_add_i32 s56, s15, s44
	s_mov_b32 s57, m0
	s_mov_b32 m0, s56
	s_nop 0
	global_load_lds_dwordx4 v[178:179], off
	s_mov_b32 m0, s57
	s_add_i32 s15, s15, s45
	s_mov_b32 s56, m0
	s_mov_b32 m0, s15
	s_nop 0
	global_load_lds_dwordx4 v[176:177], off
	s_mov_b32 m0, s56
	s_branch .LBB0_137
.Ln192_act:
	s_mul_i32 s15, s54, 0xa000
	s_add_i32 s15, s15, 0
	v_add_u32_e32 v0, s15, v204
	v_add_u32_e32 v238, v0, v209
	v_add_u32_e32 v239, v0, v210
	v_add_u32_e32 v240, v0, v213
	v_add_u32_e32 v0, v0, v214
	ds_read_b128 v[66:69], v238
	ds_read_b128 v[70:73], v238 offset:12288
	ds_read_b128 v[146:149], v239
	ds_read_b128 v[150:153], v239 offset:12288
	ds_read_b128 v[154:157], v240
	ds_read_b128 v[158:161], v240 offset:12288
	ds_read_b128 v[220:223], v0
	ds_read_b128 v[224:227], v0 offset:12288
	s_setprio 1
	s_waitcnt lgkmcnt(7)
	v_mfma_f32_32x32x16_bf16 v[82:97], v[66:69], v[98:101], 0
	s_waitcnt lgkmcnt(6)
	v_mfma_f32_32x32x16_bf16 v[66:81], v[70:73], v[98:101], 0
	s_waitcnt lgkmcnt(5)
	v_mfma_f32_32x32x16_bf16 v[82:97], v[146:149], v[102:105], v[82:97]
	s_waitcnt lgkmcnt(4)
	v_mfma_f32_32x32x16_bf16 v[66:81], v[150:153], v[102:105], v[66:81]
	s_setprio 0
	ds_read_b128 v[146:149], v239 offset:128
	ds_read_b128 v[150:153], v239 offset:12416
	ds_read_b128 v[230:233], v238 offset:12416
	ds_read_b128 v[234:237], v238 offset:128
	s_setprio 1
	s_waitcnt lgkmcnt(7)
	v_mfma_f32_32x32x16_bf16 v[82:97], v[154:157], v[106:109], v[82:97]
	s_waitcnt lgkmcnt(6)
	v_mfma_f32_32x32x16_bf16 v[66:81], v[158:161], v[106:109], v[66:81]
	s_waitcnt lgkmcnt(5)
	v_mfma_f32_32x32x16_bf16 v[82:97], v[220:223], v[110:113], v[82:97]
	s_waitcnt lgkmcnt(4)
	v_mfma_f32_32x32x16_bf16 v[66:81], v[224:227], v[110:113], v[66:81]
	s_setprio 0
	ds_read_b128 v[154:157], v240 offset:128
	ds_read_b128 v[158:161], v240 offset:12416
	ds_read_b128 v[220:223], v0 offset:128
	ds_read_b128 v[224:227], v0 offset:12416
	s_setprio 1
	s_waitcnt lgkmcnt(4)
	v_mfma_f32_32x32x16_bf16 v[82:97], v[234:237], v[114:117], v[82:97]
	v_mfma_f32_32x32x16_bf16 v[66:81], v[230:233], v[114:117], v[66:81]
	v_mfma_f32_32x32x16_bf16 v[82:97], v[146:149], v[118:121], v[82:97]
	v_mfma_f32_32x32x16_bf16 v[66:81], v[150:153], v[118:121], v[66:81]
	s_setprio 0
	ds_read_b128 v[146:149], v239 offset:256
	ds_read_b128 v[150:153], v239 offset:12544
	ds_read_b128 v[230:233], v238 offset:12544
	ds_read_b128 v[234:237], v238 offset:256
	s_setprio 1
	s_waitcnt lgkmcnt(7)
	v_mfma_f32_32x32x16_bf16 v[82:97], v[154:157], v[122:125], v[82:97]
	s_waitcnt lgkmcnt(6)
	v_mfma_f32_32x32x16_bf16 v[66:81], v[158:161], v[122:125], v[66:81]
	s_waitcnt lgkmcnt(5)
	v_mfma_f32_32x32x16_bf16 v[82:97], v[220:223], v[126:129], v[82:97]
	s_waitcnt lgkmcnt(4)
	v_mfma_f32_32x32x16_bf16 v[66:81], v[224:227], v[126:129], v[66:81]
	s_setprio 0
	ds_read_b128 v[154:157], v240 offset:256
	ds_read_b128 v[158:161], v240 offset:12544
	ds_read_b128 v[220:223], v0 offset:256
	ds_read_b128 v[224:227], v0 offset:12544
	s_setprio 1
	s_waitcnt lgkmcnt(4)
	v_mfma_f32_32x32x16_bf16 v[82:97], v[234:237], v[130:133], v[82:97]
	v_mfma_f32_32x32x16_bf16 v[66:81], v[230:233], v[130:133], v[66:81]
	v_mfma_f32_32x32x16_bf16 v[82:97], v[146:149], v[134:137], v[82:97]
	v_mfma_f32_32x32x16_bf16 v[66:81], v[150:153], v[134:137], v[66:81]
	s_setprio 0
	s_setprio 1
	s_waitcnt lgkmcnt(3)
	v_mfma_f32_32x32x16_bf16 v[82:97], v[154:157], v[138:141], v[82:97]
	s_waitcnt lgkmcnt(2)
	v_mfma_f32_32x32x16_bf16 v[66:81], v[158:161], v[138:141], v[66:81]
	s_waitcnt lgkmcnt(1)
	v_mfma_f32_32x32x16_bf16 v[82:97], v[220:223], v[142:145], v[82:97]
	s_waitcnt lgkmcnt(0)
	v_mfma_f32_32x32x16_bf16 v[66:81], v[224:227], v[142:145], v[66:81]
	s_setprio 0
	v_add3_u32 v0, s15, v205, v206
	v_add3_u32 v239, v0, v207, v208
	v_add_u32_e32 v246, v239, v211
	v_add_u32_e32 v247, v239, v215
	v_add_u32_e32 v248, v239, v216
	v_add_u32_e32 v249, v239, v217
	s_cmp_ge_u32 s14, s47
	s_cbranch_scc1 .Ln192_dmadone
	s_mul_i32 s15, s46, 0xa000
	s_add_i32 s56, s15, s41
	s_mov_b32 s57, m0
	s_mov_b32 m0, s56
	s_nop 0
	global_load_lds_dwordx4 v[184:185], off
	s_mov_b32 m0, s57
	s_add_i32 s56, s15, s42
	s_mov_b32 s57, m0
	s_mov_b32 m0, s56
	s_nop 0
	global_load_lds_dwordx4 v[182:183], off
	s_mov_b32 m0, s57
	s_add_i32 s56, s15, s43
	s_mov_b32 s57, m0
	s_mov_b32 m0, s56
	s_nop 0
	global_load_lds_dwordx4 v[180:181], off
	s_mov_b32 m0, s57
	s_add_i32 s56, s15, s44
	s_mov_b32 s57, m0
	s_mov_b32 m0, s56
	s_nop 0
	global_load_lds_dwordx4 v[178:179], off
	s_mov_b32 m0, s57
	s_add_i32 s15, s15, s45
	s_mov_b32 s56, m0
	s_mov_b32 m0, s15
	s_nop 0
	global_load_lds_dwordx4 v[176:177], off
	s_mov_b32 m0, s56
; template <int DK>
; DI void attn_pass(const AttnSrc& s, const int q0, const float sc, LAS unsigned char* lds, f32x16 (&O)[4]) {
;     ...
;           const s16x4 lo = __builtin_bit_cast(s16x4, __builtin_amdgcn_ds_read_tr16_b64_v4i16((LAS s16x4*)(Vb + vcol + ks * 16 * 256)));
;           const s16x4 hi = __builtin_bit_cast(s16x4, __builtin_amdgcn_ds_read_tr16_b64_v4i16((LAS s16x4*)(Vb + vcol + (ks * 16 + 8) * 256)));
;           vf[slot][ks] = __builtin_shufflevector(lo, hi, 0, 1, 2, 3, 4, 5, 6, 7);
;         }
;       };
;       vload(0, 0);
;       if (64 * t + 63 > qw0) {
;         const int qa = qw0 + r, kbase = 64 * t + 4 * h;
; #pragma unroll
;         for (int j = 0; j < 16; ++j) { const int kv = kbase + (j & 3) + 8 * (j >> 2); if (kv > qa) p0[j] = -INFINITY; if (kv + 32 > qa) p1[j] = -INFINITY; }
;       }
;       asm volatile("s_nop 15\n\ts_nop 7" : "+v"(p0), "+v"(p1));
;       float mx;
;       { float ma = max3f(p0[0], p0[1], p1[0]), mb = max3f(p0[2], p0[3], p1[1]); ma = max3f(ma, p1[2], p1[3]);
; #pragma unroll
;         for (int j = 4; j < 16; j += 4) { ma = max3f(ma, p0[j], p0[j + 1]); mb = max3f(mb, p0[j + 2], p0[j + 3]); ma = max3f(ma, p1[j], p1[j + 1]); mb = max3f(mb, p1[j + 2], p1[j + 3]); }
;         mx = fmaxf(ma, mb); }
;       { auto rr = __builtin_amdgcn_permlane32_swap(__float_as_uint(mx), __float_as_uint(mx), false, false); mx = fmaxf(__uint_as_float(rr[0]), __uint_as_float(rr[1])); }
;       float rs = 0.f;
;       if (REL) {
;         const bool grow = (mx > 8.f) || (t == 0);
;         if (__builtin_amdgcn_ballot_w64(grow) != 0ull) {
;           const float dl = grow ? mx : 0.f;
;           const float alpha = __builtin_amdgcn_exp2f(-dl);
;           mrun += dl; lrun *= alpha;
; #pragma unroll
;           for (int j = 0; j < 16; ++j) { p0[j] -= dl; p1[j] -= dl; negm[j] = -mrun; }
;           asm volatile("" : "+v"(negm));
; #pragma unroll
;           for (int i = 0; i < 4; ++i)
; #pragma unroll
;             for (int j = 0; j < 16; ++j) O[i][j] *= alpha;
;         }
; #pragma unroll
;         for (int j = 0; j < 16; ++j) { p0[j] = __builtin_amdgcn_exp2f(p0[j]); p1[j] = __builtin_amdgcn_exp2f(p1[j]); rs += p0[j] + p1[j]; }
;       } else {
;         const float cand = mx * sc;
;         const bool grow = cand > mrun + 8.f;
;         if (__builtin_amdgcn_ballot_w64(grow) != 0ull) {
;           const float mnew = grow ? cand : mrun;
.Ln192_dmadone:
	ds_read_b64_tr_b16 v[146:147], v246 offset:24576
	ds_read_b64_tr_b16 v[148:149], v246 offset:26624
	ds_read_b64_tr_b16 v[150:151], v247 offset:24576
	ds_read_b64_tr_b16 v[152:153], v247 offset:26624
	ds_read_b64_tr_b16 v[154:155], v248 offset:24576
	ds_read_b64_tr_b16 v[156:157], v248 offset:26624
	ds_read_b64_tr_b16 v[158:159], v249 offset:24576
	ds_read_b64_tr_b16 v[160:161], v249 offset:26624
	s_cmp_le_i32 s55, s40
	s_cbranch_scc1 .Ln192_nomask
	v_add_u32_e32 v0, s55, v212
	v_subrev_u32_e32 v222, 31, v0
	v_subrev_u32_e32 v221, 63, v0
	v_cmp_le_i32_e32 vcc, v222, v167
	s_nop 1
	v_cndmask_b32_e32 v66, v201, v66, vcc
	v_cmp_lt_i32_e32 vcc, v221, v167
	s_nop 1
	v_cndmask_b32_e32 v83, v201, v83, vcc
	v_cmp_le_i32_e32 vcc, v221, v167
	v_subrev_u32_e32 v221, 30, v0
	s_nop 0
	v_cndmask_b32_e32 v82, v201, v82, vcc
	v_cmp_le_i32_e32 vcc, v221, v167
	v_subrev_u32_e32 v221, 61, v0
	s_nop 0
	v_cndmask_b32_e32 v67, v201, v67, vcc
	v_cmp_le_i32_e32 vcc, v221, v167
	v_subrev_u32_e32 v221, 29, v0
	s_nop 0
	v_cndmask_b32_e32 v84, v201, v84, vcc
	v_cmp_le_i32_e32 vcc, v221, v167
	v_subrev_u32_e32 v221, 60, v0
	s_nop 0
	v_cndmask_b32_e32 v68, v201, v68, vcc
	v_cmp_le_i32_e32 vcc, v221, v167
	v_subrev_u32_e32 v221, 28, v0
	s_nop 0
	v_cndmask_b32_e32 v85, v201, v85, vcc
	v_cmp_le_i32_e32 vcc, v221, v167
	v_subrev_u32_e32 v221, 55, v0
	s_nop 0
	v_cndmask_b32_e32 v69, v201, v69, vcc
	v_cmp_le_i32_e32 vcc, v221, v167
	v_subrev_u32_e32 v221, 23, v0
	s_nop 0
	v_cndmask_b32_e32 v86, v201, v86, vcc
	v_cmp_le_i32_e32 vcc, v221, v167
	v_subrev_u32_e32 v221, 54, v0
	s_nop 0
	v_cndmask_b32_e32 v70, v201, v70, vcc
	v_cmp_le_i32_e32 vcc, v221, v167
	v_subrev_u32_e32 v221, 22, v0
	s_nop 0
	v_cndmask_b32_e32 v87, v201, v87, vcc
	v_cmp_le_i32_e32 vcc, v221, v167
	v_subrev_u32_e32 v221, 53, v0
	s_nop 0
	v_cndmask_b32_e32 v71, v201, v71, vcc
	v_cmp_le_i32_e32 vcc, v221, v167
	v_subrev_u32_e32 v221, 21, v0
	s_nop 0
	v_cndmask_b32_e32 v88, v201, v88, vcc
	v_cmp_le_i32_e32 vcc, v221, v167
	v_subrev_u32_e32 v221, 52, v0
	s_nop 0
	v_cndmask_b32_e32 v72, v201, v72, vcc
	v_cmp_le_i32_e32 vcc, v221, v167
	v_subrev_u32_e32 v221, 20, v0
	s_nop 0
	v_cndmask_b32_e32 v89, v201, v89, vcc
	v_cmp_le_i32_e32 vcc, v221, v167
	v_subrev_u32_e32 v221, 47, v0
	s_nop 0
	v_cndmask_b32_e32 v73, v201, v73, vcc
	v_cmp_le_i32_e32 vcc, v221, v167
	v_add_u32_e32 v221, -15, v0
	s_nop 0
	v_cndmask_b32_e32 v90, v201, v90, vcc
	v_cmp_le_i32_e32 vcc, v221, v167
	v_subrev_u32_e32 v221, 46, v0
	s_nop 0
	v_cndmask_b32_e32 v74, v201, v74, vcc
	v_cmp_le_i32_e32 vcc, v221, v167
	v_add_u32_e32 v221, -14, v0
	s_nop 0
	v_cndmask_b32_e32 v91, v201, v91, vcc
	v_cmp_le_i32_e32 vcc, v221, v167
	v_subrev_u32_e32 v221, 45, v0
	s_nop 0
	v_cndmask_b32_e32 v75, v201, v75, vcc
	v_cmp_le_i32_e32 vcc, v221, v167
	v_add_u32_e32 v221, -13, v0
	s_nop 0
	v_cndmask_b32_e32 v92, v201, v92, vcc
	v_cmp_le_i32_e32 vcc, v221, v167
	v_subrev_u32_e32 v221, 44, v0
	s_nop 0
	v_cndmask_b32_e32 v76, v201, v76, vcc
	v_cmp_le_i32_e32 vcc, v221, v167
	v_add_u32_e32 v221, -12, v0
	s_nop 0
	v_cndmask_b32_e32 v93, v201, v93, vcc
	v_cmp_le_i32_e32 vcc, v221, v167
	v_subrev_u32_e32 v221, 39, v0
	s_nop 0
	v_cndmask_b32_e32 v77, v201, v77, vcc
	v_cmp_le_i32_e32 vcc, v221, v167
	v_add_u32_e32 v221, -7, v0
	s_nop 0
	v_cndmask_b32_e32 v94, v201, v94, vcc
	v_cmp_le_i32_e32 vcc, v221, v167
	v_subrev_u32_e32 v221, 38, v0
	s_nop 0
	v_cndmask_b32_e32 v78, v201, v78, vcc
	v_cmp_le_i32_e32 vcc, v221, v167
	v_add_u32_e32 v221, -6, v0
	s_nop 0
	v_cndmask_b32_e32 v95, v201, v95, vcc
	v_cmp_le_i32_e32 vcc, v221, v167
	v_subrev_u32_e32 v221, 37, v0
	s_nop 0
	v_cndmask_b32_e32 v79, v201, v79, vcc
	v_cmp_le_i32_e32 vcc, v221, v167
	v_add_u32_e32 v221, -5, v0
	s_nop 0
	v_cndmask_b32_e32 v96, v201, v96, vcc
	v_cmp_le_i32_e32 vcc, v221, v167
	v_subrev_u32_e32 v221, 36, v0
	v_add_u32_e32 v0, -4, v0
	v_cndmask_b32_e32 v80, v201, v80, vcc
	v_cmp_le_i32_e32 vcc, v221, v167
	s_nop 1
	v_cndmask_b32_e32 v97, v201, v97, vcc
	v_cmp_le_i32_e32 vcc, v0, v167
	s_nop 1
	v_cndmask_b32_e32 v81, v201, v81, vcc
.Ln192_nomask:
	s_nop 0
	v_max3_f32 v0, v82, v83, v66
	v_max3_f32 v221, v84, v85, v67
	s_nop 0
	v_max3_f32 v0, v0, v68, v69
	v_max3_f32 v221, v221, v88, v89
	s_nop 0
	v_max3_f32 v0, v0, v86, v87
	v_max3_f32 v221, v221, v72, v73
	s_nop 0
	v_max3_f32 v0, v0, v70, v71
	v_max3_f32 v221, v221, v92, v93
	s_nop 0
	v_max3_f32 v0, v0, v90, v91
	v_max3_f32 v221, v221, v76, v77
	s_nop 0
	v_max3_f32 v0, v0, v74, v75
	v_max3_f32 v221, v221, v96, v97
	s_nop 0
	v_max3_f32 v0, v0, v94, v95
	v_max3_f32 v221, v221, v80, v81
	s_nop 0
	v_max3_f32 v0, v0, v78, v79
	v_max_f32_e32 v221, v221, v221
	v_max_f32_e32 v0, v0, v0
	v_max_f32_e32 v0, v0, v221
	v_mov_b32_e32 v221, v0
	s_nop 1
	v_permlane32_swap_b32_e32 v0, v221
	v_max_f32_e32 v221, v221, v221
	v_max_f32_e32 v0, v0, v0
	v_max_f32_e32 v0, v0, v221
	v_mul_f32_e32 v0, 0x3dd53b94, v0
	v_add_f32_e32 v221, 0x41000000, v219
	v_cmp_gt_f32_e32 vcc, v0, v221
	s_cbranch_vccz .Ln192_exp
	s_nop 0
	v_cndmask_b32_e32 v221, v219, v0, vcc
	v_sub_f32_e32 v0, v219, v221
	v_exp_f32_e32 v0, v0
	v_mov_b32_e32 v219, v221
	v_pk_mul_f32 v[64:65], v[64:65], v[0:1] op_sel_hi:[1,0]
	v_pk_mul_f32 v[62:63], v[62:63], v[0:1] op_sel_hi:[1,0]
	v_pk_mul_f32 v[60:61], v[60:61], v[0:1] op_sel_hi:[1,0]
	v_pk_mul_f32 v[58:59], v[58:59], v[0:1] op_sel_hi:[1,0]
	v_pk_mul_f32 v[56:57], v[56:57], v[0:1] op_sel_hi:[1,0]
	v_pk_mul_f32 v[54:55], v[54:55], v[0:1] op_sel_hi:[1,0]
	v_pk_mul_f32 v[52:53], v[52:53], v[0:1] op_sel_hi:[1,0]
	v_pk_mul_f32 v[50:51], v[50:51], v[0:1] op_sel_hi:[1,0]
	v_pk_mul_f32 v[48:49], v[48:49], v[0:1] op_sel_hi:[1,0]
	v_pk_mul_f32 v[46:47], v[46:47], v[0:1] op_sel_hi:[1,0]
	v_pk_mul_f32 v[44:45], v[44:45], v[0:1] op_sel_hi:[1,0]
	v_pk_mul_f32 v[42:43], v[42:43], v[0:1] op_sel_hi:[1,0]
	v_pk_mul_f32 v[40:41], v[40:41], v[0:1] op_sel_hi:[1,0]
	v_pk_mul_f32 v[38:39], v[38:39], v[0:1] op_sel_hi:[1,0]
	v_pk_mul_f32 v[36:37], v[36:37], v[0:1] op_sel_hi:[1,0]
	v_pk_mul_f32 v[34:35], v[34:35], v[0:1] op_sel_hi:[1,0]
	v_pk_mul_f32 v[32:33], v[32:33], v[0:1] op_sel_hi:[1,0]
	v_pk_mul_f32 v[30:31], v[30:31], v[0:1] op_sel_hi:[1,0]
	v_pk_mul_f32 v[28:29], v[28:29], v[0:1] op_sel_hi:[1,0]
	v_pk_mul_f32 v[26:27], v[26:27], v[0:1] op_sel_hi:[1,0]
	v_pk_mul_f32 v[24:25], v[24:25], v[0:1] op_sel_hi:[1,0]
	v_pk_mul_f32 v[22:23], v[22:23], v[0:1] op_sel_hi:[1,0]
	v_pk_mul_f32 v[20:21], v[20:21], v[0:1] op_sel_hi:[1,0]
	v_pk_mul_f32 v[18:19], v[18:19], v[0:1] op_sel_hi:[1,0]
	v_pk_mul_f32 v[16:17], v[16:17], v[0:1] op_sel_hi:[1,0]
	v_pk_mul_f32 v[14:15], v[14:15], v[0:1] op_sel_hi:[1,0]
	v_pk_mul_f32 v[12:13], v[12:13], v[0:1] op_sel_hi:[1,0]
	v_pk_mul_f32 v[10:11], v[10:11], v[0:1] op_sel_hi:[1,0]
	v_pk_mul_f32 v[8:9], v[8:9], v[0:1] op_sel_hi:[1,0]
	v_pk_mul_f32 v[6:7], v[6:7], v[0:1] op_sel_hi:[1,0]
	v_pk_mul_f32 v[4:5], v[4:5], v[0:1] op_sel_hi:[1,0]
	v_pk_mul_f32 v[2:3], v[2:3], v[0:1] op_sel_hi:[1,0]
	v_mul_f32_e32 v218, v218, v0
; DI unsigned cvt_pk_bf16(float lo, float hi) { unsigned r; asm volatile("v_cvt_pk_bf16_f32 %0, %1, %2" : "=v"(r) : "v"(lo), "v"(hi)); return r; }
; template <int DK>
; DI void attn_pass(const AttnSrc& s, const int q0, const float sc, LAS unsigned char* lds, f32x16 (&O)[4]) {
;     ...
; #pragma unroll
;         for (int j = 0; j < 16; ++j) { p0[j] = __builtin_amdgcn_exp2f(p0[j] * sc - mrun); p1[j] = __builtin_amdgcn_exp2f(p1[j] * sc - mrun); rs += p0[j] + p1[j]; }
;       }
;       lrun += rs;
;       bf16x8 pb[4];
;       { u32x4 w;
;         w.x = cvt_pk_bf16(p0[0], p0[1]); w.y = cvt_pk_bf16(p0[2], p0[3]); w.z = cvt_pk_bf16(p0[4], p0[5]); w.w = cvt_pk_bf16(p0[6], p0[7]); pb[0] = __builtin_bit_cast(bf16x8, w);
;         w.x = cvt_pk_bf16(p0[8], p0[9]); w.y = cvt_pk_bf16(p0[10], p0[11]); w.z = cvt_pk_bf16(p0[12], p0[13]); w.w = cvt_pk_bf16(p0[14], p0[15]); pb[1] = __builtin_bit_cast(bf16x8, w);
;         w.x = cvt_pk_bf16(p1[0], p1[1]); w.y = cvt_pk_bf16(p1[2], p1[3]); w.z = cvt_pk_bf16(p1[4], p1[5]); w.w = cvt_pk_bf16(p1[6], p1[7]); pb[2] = __builtin_bit_cast(bf16x8, w);
;         w.x = cvt_pk_bf16(p1[8], p1[9]); w.y = cvt_pk_bf16(p1[10], p1[11]); w.z = cvt_pk_bf16(p1[12], p1[13]); w.w = cvt_pk_bf16(p1[14], p1[15]); pb[3] = __builtin_bit_cast(bf16x8, w); }
; #pragma unroll
;       for (int vt = 0; vt < 4; ++vt) {
;         if (vt + 1 < 4) vload(vt + 1, (vt + 1) & 1);
;         __builtin_amdgcn_s_setprio(1);
; #pragma unroll
;         for (int ks = 0; ks < 4; ++ks) O[vt] = __builtin_amdgcn_mfma_f32_32x32x16_bf16(vf[vt & 1][ks], pb[ks], O[vt], 0, 0, 0);
;         __builtin_amdgcn_s_setprio(0);
;       }
.Ln192_exp:
	v_fma_f32 v82, v82, s61, -v219
	v_fma_f32 v83, v83, s61, -v219
	v_fma_f32 v84, v84, s61, -v219
	v_fma_f32 v85, v85, s61, -v219
	v_fma_f32 v86, v86, s61, -v219
	v_fma_f32 v87, v87, s61, -v219
	v_fma_f32 v88, v88, s61, -v219
	v_fma_f32 v89, v89, s61, -v219
	v_exp_f32_e32 v82, v82
	v_exp_f32_e32 v83, v83
	v_exp_f32_e32 v84, v84
	v_exp_f32_e32 v85, v85
	v_exp_f32_e32 v86, v86
	v_exp_f32_e32 v87, v87
	v_exp_f32_e32 v88, v88
	v_exp_f32_e32 v89, v89
	v_add_f32_e32 v0, v82, v83
	v_add_f32_e32 v238, v84, v85
	v_add_f32_e32 v0, v0, v86
	v_add_f32_e32 v238, v238, v87
	v_add_f32_e32 v0, v0, v88
	v_add_f32_e32 v238, v238, v89
	v_cvt_pk_bf16_f32 v82, v82, v83
	v_cvt_pk_bf16_f32 v83, v84, v85
	v_cvt_pk_bf16_f32 v84, v86, v87
	v_cvt_pk_bf16_f32 v85, v88, v89
	ds_read_b64_tr_b16 v[220:221], v246 offset:28672
	ds_read_b64_tr_b16 v[222:223], v246 offset:30720
	ds_read_b64_tr_b16 v[224:225], v247 offset:28672
	ds_read_b64_tr_b16 v[226:227], v247 offset:30720
	ds_read_b64_tr_b16 v[230:231], v248 offset:28672
	ds_read_b64_tr_b16 v[232:233], v248 offset:30720
	ds_read_b64_tr_b16 v[234:235], v249 offset:28672
	ds_read_b64_tr_b16 v[236:237], v249 offset:30720
	s_setprio 1
	s_waitcnt lgkmcnt(14)
	v_mfma_f32_32x32x16_bf16 v[50:65], v[146:149], v[82:85], v[50:65]
	s_waitcnt lgkmcnt(12)
	v_mfma_f32_32x32x16_bf16 v[34:49], v[150:153], v[82:85], v[34:49]
	s_waitcnt lgkmcnt(10)
	v_mfma_f32_32x32x16_bf16 v[18:33], v[154:157], v[82:85], v[18:33]
	s_waitcnt lgkmcnt(8)
	v_mfma_f32_32x32x16_bf16 v[2:17], v[158:161], v[82:85], v[2:17]
	v_fma_f32 v90, v90, s61, -v219
	v_fma_f32 v91, v91, s61, -v219
	v_fma_f32 v92, v92, s61, -v219
	v_fma_f32 v93, v93, s61, -v219
	v_fma_f32 v94, v94, s61, -v219
	v_fma_f32 v95, v95, s61, -v219
	v_fma_f32 v96, v96, s61, -v219
	v_fma_f32 v97, v97, s61, -v219
	v_exp_f32_e32 v90, v90
	v_exp_f32_e32 v91, v91
	v_exp_f32_e32 v92, v92
	v_exp_f32_e32 v93, v93
	v_exp_f32_e32 v94, v94
	v_exp_f32_e32 v95, v95
	v_exp_f32_e32 v96, v96
	v_exp_f32_e32 v97, v97
	v_add_f32_e32 v0, v0, v90
	v_add_f32_e32 v238, v238, v91
	v_add_f32_e32 v0, v0, v92
	v_add_f32_e32 v238, v238, v93
	v_add_f32_e32 v0, v0, v94
	v_add_f32_e32 v238, v238, v95
	v_add_f32_e32 v0, v0, v96
	v_add_f32_e32 v238, v238, v97
	v_cvt_pk_bf16_f32 v86, v90, v91
	v_cvt_pk_bf16_f32 v87, v92, v93
	v_cvt_pk_bf16_f32 v88, v94, v95
	v_cvt_pk_bf16_f32 v89, v96, v97
	ds_read_b64_tr_b16 v[146:147], v246 offset:32768
	ds_read_b64_tr_b16 v[148:149], v246 offset:34816
	ds_read_b64_tr_b16 v[150:151], v247 offset:32768
	ds_read_b64_tr_b16 v[152:153], v247 offset:34816
	ds_read_b64_tr_b16 v[154:155], v248 offset:32768
	ds_read_b64_tr_b16 v[156:157], v248 offset:34816
	ds_read_b64_tr_b16 v[158:159], v249 offset:32768
	ds_read_b64_tr_b16 v[160:161], v249 offset:34816
	s_waitcnt lgkmcnt(14)
	v_mfma_f32_32x32x16_bf16 v[50:65], v[220:223], v[86:89], v[50:65]
	s_waitcnt lgkmcnt(12)
	v_mfma_f32_32x32x16_bf16 v[34:49], v[224:227], v[86:89], v[34:49]
	s_waitcnt lgkmcnt(10)
	v_mfma_f32_32x32x16_bf16 v[18:33], v[230:233], v[86:89], v[18:33]
	s_waitcnt lgkmcnt(8)
	v_mfma_f32_32x32x16_bf16 v[2:17], v[234:237], v[86:89], v[2:17]
	v_fma_f32 v66, v66, s61, -v219
	v_fma_f32 v67, v67, s61, -v219
	v_fma_f32 v68, v68, s61, -v219
	v_fma_f32 v69, v69, s61, -v219
	v_fma_f32 v70, v70, s61, -v219
	v_fma_f32 v71, v71, s61, -v219
	v_fma_f32 v72, v72, s61, -v219
	v_fma_f32 v73, v73, s61, -v219
	v_exp_f32_e32 v66, v66
	v_exp_f32_e32 v67, v67
	v_exp_f32_e32 v68, v68
	v_exp_f32_e32 v69, v69
	v_exp_f32_e32 v70, v70
	v_exp_f32_e32 v71, v71
	v_exp_f32_e32 v72, v72
	v_exp_f32_e32 v73, v73
	v_add_f32_e32 v0, v0, v66
	v_add_f32_e32 v238, v238, v67
	v_add_f32_e32 v0, v0, v68
	v_add_f32_e32 v238, v238, v69
	v_add_f32_e32 v0, v0, v70
	v_add_f32_e32 v238, v238, v71
	v_add_f32_e32 v0, v0, v72
	v_add_f32_e32 v238, v238, v73
	v_cvt_pk_bf16_f32 v66, v66, v67
	v_cvt_pk_bf16_f32 v67, v68, v69
	v_cvt_pk_bf16_f32 v68, v70, v71
	v_cvt_pk_bf16_f32 v69, v72, v73
	ds_read_b64_tr_b16 v[220:221], v246 offset:36864
	ds_read_b64_tr_b16 v[222:223], v246 offset:38912
	ds_read_b64_tr_b16 v[224:225], v247 offset:36864
	ds_read_b64_tr_b16 v[226:227], v247 offset:38912
	ds_read_b64_tr_b16 v[230:231], v248 offset:36864
	ds_read_b64_tr_b16 v[232:233], v248 offset:38912
	ds_read_b64_tr_b16 v[234:235], v249 offset:36864
	ds_read_b64_tr_b16 v[236:237], v249 offset:38912
	s_waitcnt lgkmcnt(14)
	v_mfma_f32_32x32x16_bf16 v[50:65], v[146:149], v[66:69], v[50:65]
	s_waitcnt lgkmcnt(12)
	v_mfma_f32_32x32x16_bf16 v[34:49], v[150:153], v[66:69], v[34:49]
	s_waitcnt lgkmcnt(10)
	v_mfma_f32_32x32x16_bf16 v[18:33], v[154:157], v[66:69], v[18:33]
	s_waitcnt lgkmcnt(8)
	v_mfma_f32_32x32x16_bf16 v[2:17], v[158:161], v[66:69], v[2:17]
	v_fma_f32 v74, v74, s61, -v219
	v_fma_f32 v75, v75, s61, -v219
	v_fma_f32 v76, v76, s61, -v219
	v_fma_f32 v77, v77, s61, -v219
	v_fma_f32 v78, v78, s61, -v219
	v_fma_f32 v79, v79, s61, -v219
	v_fma_f32 v80, v80, s61, -v219
	v_fma_f32 v81, v81, s61, -v219
	v_exp_f32_e32 v74, v74
	v_exp_f32_e32 v75, v75
	v_exp_f32_e32 v76, v76
	v_exp_f32_e32 v77, v77
	v_exp_f32_e32 v78, v78
	v_exp_f32_e32 v79, v79
	v_exp_f32_e32 v80, v80
	v_exp_f32_e32 v81, v81
	v_add_f32_e32 v0, v0, v74
	v_add_f32_e32 v238, v238, v75
	v_add_f32_e32 v0, v0, v76
	v_add_f32_e32 v238, v238, v77
	v_add_f32_e32 v0, v0, v78
	v_add_f32_e32 v238, v238, v79
	v_add_f32_e32 v0, v0, v80
	v_add_f32_e32 v238, v238, v81
	v_cvt_pk_bf16_f32 v70, v74, v75
	v_cvt_pk_bf16_f32 v71, v76, v77
	v_cvt_pk_bf16_f32 v72, v78, v79
	v_cvt_pk_bf16_f32 v73, v80, v81
	s_nop 1
	s_waitcnt lgkmcnt(6)
	v_mfma_f32_32x32x16_bf16 v[50:65], v[220:223], v[70:73], v[50:65]
	s_waitcnt lgkmcnt(4)
	v_mfma_f32_32x32x16_bf16 v[34:49], v[224:227], v[70:73], v[34:49]
	s_waitcnt lgkmcnt(2)
	v_mfma_f32_32x32x16_bf16 v[18:33], v[230:233], v[70:73], v[18:33]
	s_waitcnt lgkmcnt(0)
	v_mfma_f32_32x32x16_bf16 v[2:17], v[234:237], v[70:73], v[2:17]
	s_setprio 0
	v_add_f32_e32 v0, v0, v238
	v_add_f32_e32 v218, v218, v0
	s_branch .LBB0_137
